# attention: the three unmasked 128-key chunks rewritten as straight-line software-pipelined code (exp/cvt/rowsum of one query block under the other block's MFMAs, K/V fragment prefetch)
# speedup vs baseline: 1.0169x; 1.0062x over previous
; #define LAS __attribute__((address_space(3)))
; __device__ __forceinline__ bool attn_unit(const Ptrs& P, LAS unsigned char* lds, int unit, int tid, int wave, int lane, bool pre, int nxt) {
;     ...
;         const LAS unsigned char* Kl = lds + (c % 3) * AT_BUF; const LAS unsigned char* Vl = Kl + AT_KB;
; #pragma unroll 1
;         for (int kt = 0; kt < 4; ++kt) {
;             if (c == 0 && 32 * kt + 31 < q0) continue;
;             if (c == 2 && 32 * kt > q0 + 63) continue;
;             bf16x8_t kf[4], vf[2][2];
; #pragma unroll
;             for (int ds = 0; ds < 4; ++ds) kf[ds] = *(const LAS bf16x8_t*)(Kl + (32 * kt + r) * AT_KP + (16 * ds + 8 * hh) * 2);
; #pragma unroll
;             for (int db = 0; db < 2; ++db)
; #pragma unroll
;                 for (int s = 0; s < 2; ++s) vf[db][s] = *(const LAS bf16x8_t*)(Vl + (32 * db + r) * AT_VP + (32 * kt + 16 * s + 8 * hh) * 2);
; #pragma unroll
;             for (int cb = 0; cb < 2; ++cb) {
;                 const int dq = 32 * kt - (q0 + 32 * cb);
;                 if ((c == 0 && dq < 0) || (c == 2 && dq > 0)) continue;
;                 const bool diag = (c == 0 || c == 2) && dq == 0;
;                 f32x16 st = MFMA32(kf[0], qf[cb][0], negm);
;                 st = MFMA32(kf[1], qf[cb][1], st); st = MFMA32(kf[2], qf[cb][2], st); st = MFMA32(kf[3], qf[cb][3], st);
;                 float p[16];
; #pragma unroll
;                 for (int i = 0; i < 16; ++i) p[i] = __builtin_amdgcn_exp2f(st[i]);
;                 if (diag) {
;                     const int thr = r - 4 * hh;
; #pragma unroll
;                     for (int i = 0; i < 16; ++i) { const bool vis = c == 0 ? crow(i, 0) >= thr : crow(i, 0) <= thr; p[i] = vis ? p[i] : 0.f; }
;                 }
;                 float s4 = 0.f;
; #pragma unroll
;                 for (int i = 0; i < 16; ++i) s4 += p[i];
;                 rs[cb] += s4;
; #pragma unroll
;                 for (int s = 0; s < 2; ++s) {
;                     u32x4 w; w.x = cvtpk(p[8 * s], p[8 * s + 1]); w.y = cvtpk(p[8 * s + 2], p[8 * s + 3]); w.z = cvtpk(p[8 * s + 4], p[8 * s + 5]); w.w = cvtpk(p[8 * s + 6], p[8 * s + 7]);
;                     const bf16x8_t pb = __builtin_bit_cast(bf16x8_t, w);
;                     o[0][cb] = MFMA32(vf[0][s], pb, o[0][cb]); o[1][cb] = MFMA32(vf[1][s], pb, o[1][cb]);
;                 }
;             }
;         }
.LBB9_364:
	ds_read_b128 v[238:241], v199 offset:0
	ds_read_b128 v[242:245], v199 offset:32
	ds_read_b128 v[246:249], v199 offset:64
	ds_read_b128 v[204:207], v199 offset:96
	s_waitcnt lgkmcnt(0)
	v_mfma_f32_32x32x16_bf16 v[82:97], v[238:241], v[114:117], v[18:33]
	v_mfma_f32_32x32x16_bf16 v[82:97], v[242:245], v[118:121], v[82:97]
	v_mfma_f32_32x32x16_bf16 v[82:97], v[246:249], v[122:125], v[82:97]
	v_mfma_f32_32x32x16_bf16 v[82:97], v[204:207], v[126:129], v[82:97]
	v_mfma_f32_32x32x16_bf16 v[98:113], v[238:241], v[130:133], v[18:33]
	v_mfma_f32_32x32x16_bf16 v[98:113], v[242:245], v[134:137], v[98:113]
	v_mfma_f32_32x32x16_bf16 v[98:113], v[246:249], v[138:141], v[98:113]
	v_mfma_f32_32x32x16_bf16 v[98:113], v[204:207], v[142:145], v[98:113]
	ds_read_b128 v[146:149], v198 offset:0
	ds_read_b128 v[150:153], v198 offset:32
	ds_read_b128 v[154:157], v197 offset:0
	ds_read_b128 v[158:161], v197 offset:32
	ds_read_b128 v[238:241], v199 offset:4608
	ds_read_b128 v[242:245], v199 offset:4640
	ds_read_b128 v[246:249], v199 offset:4672
	ds_read_b128 v[204:207], v199 offset:4704
	v_exp_f32_e32 v82, v82
	v_exp_f32_e32 v83, v83
	v_exp_f32_e32 v84, v84
	v_exp_f32_e32 v85, v85
	v_exp_f32_e32 v86, v86
	v_exp_f32_e32 v87, v87
	v_exp_f32_e32 v88, v88
	v_exp_f32_e32 v89, v89
	v_exp_f32_e32 v90, v90
	v_exp_f32_e32 v91, v91
	v_exp_f32_e32 v92, v92
	v_exp_f32_e32 v93, v93
	v_exp_f32_e32 v94, v94
	v_exp_f32_e32 v95, v95
	v_exp_f32_e32 v96, v96
	v_exp_f32_e32 v97, v97
	v_add_f32_e32 v183, v82, v183
	v_add_f32_e32 v183, v83, v183
	v_add_f32_e32 v183, v84, v183
	v_add_f32_e32 v183, v85, v183
	v_add_f32_e32 v183, v86, v183
	v_add_f32_e32 v183, v87, v183
	v_add_f32_e32 v183, v88, v183
	v_add_f32_e32 v183, v89, v183
	v_add_f32_e32 v183, v90, v183
	v_add_f32_e32 v183, v91, v183
	v_add_f32_e32 v183, v92, v183
	v_add_f32_e32 v183, v93, v183
	v_add_f32_e32 v183, v94, v183
	v_add_f32_e32 v183, v95, v183
	v_add_f32_e32 v183, v96, v183
	v_add_f32_e32 v183, v97, v183
	v_cvt_pk_bf16_f32 v82, v82, v83
	v_cvt_pk_bf16_f32 v83, v84, v85
	v_cvt_pk_bf16_f32 v84, v86, v87
	v_cvt_pk_bf16_f32 v85, v88, v89
	v_cvt_pk_bf16_f32 v86, v90, v91
	v_cvt_pk_bf16_f32 v87, v92, v93
	v_cvt_pk_bf16_f32 v88, v94, v95
	v_cvt_pk_bf16_f32 v89, v96, v97
	s_nop 0
	s_waitcnt lgkmcnt(4)
	v_mfma_f32_32x32x16_bf16 v[66:81], v[146:149], v[82:85], v[66:81]
	v_mfma_f32_32x32x16_bf16 v[50:65], v[154:157], v[82:85], v[50:65]
	v_exp_f32_e32 v98, v98
	v_exp_f32_e32 v99, v99
	v_exp_f32_e32 v100, v100
	v_exp_f32_e32 v101, v101
	v_exp_f32_e32 v102, v102
	v_mfma_f32_32x32x16_bf16 v[66:81], v[150:153], v[86:89], v[66:81]
	v_exp_f32_e32 v103, v103
	v_exp_f32_e32 v104, v104
	v_exp_f32_e32 v105, v105
	v_exp_f32_e32 v106, v106
	v_exp_f32_e32 v107, v107
	v_mfma_f32_32x32x16_bf16 v[50:65], v[158:161], v[86:89], v[50:65]
	v_exp_f32_e32 v108, v108
	v_exp_f32_e32 v109, v109
	v_exp_f32_e32 v110, v110
	v_exp_f32_e32 v111, v111
	v_exp_f32_e32 v112, v112
	s_waitcnt lgkmcnt(0)
	v_mfma_f32_32x32x16_bf16 v[82:97], v[238:241], v[114:117], v[18:33]
	v_exp_f32_e32 v113, v113
	v_add_f32_e32 v182, v98, v182
	v_add_f32_e32 v182, v99, v182
	v_add_f32_e32 v182, v100, v182
	v_add_f32_e32 v182, v101, v182
	v_mfma_f32_32x32x16_bf16 v[82:97], v[242:245], v[118:121], v[82:97]
	v_add_f32_e32 v182, v102, v182
	v_add_f32_e32 v182, v103, v182
	v_add_f32_e32 v182, v104, v182
	v_add_f32_e32 v182, v105, v182
	v_add_f32_e32 v182, v106, v182
	v_mfma_f32_32x32x16_bf16 v[82:97], v[246:249], v[122:125], v[82:97]
	v_add_f32_e32 v182, v107, v182
	v_add_f32_e32 v182, v108, v182
	v_add_f32_e32 v182, v109, v182
	v_add_f32_e32 v182, v110, v182
	v_add_f32_e32 v182, v111, v182
	v_mfma_f32_32x32x16_bf16 v[82:97], v[204:207], v[126:129], v[82:97]
	v_add_f32_e32 v182, v112, v182
	v_add_f32_e32 v182, v113, v182
	v_cvt_pk_bf16_f32 v98, v98, v99
	v_cvt_pk_bf16_f32 v99, v100, v101
	v_cvt_pk_bf16_f32 v100, v102, v103
	v_cvt_pk_bf16_f32 v101, v104, v105
	v_cvt_pk_bf16_f32 v102, v106, v107
	v_cvt_pk_bf16_f32 v103, v108, v109
	v_cvt_pk_bf16_f32 v104, v110, v111
	v_cvt_pk_bf16_f32 v105, v112, v113
	s_nop 0
	v_mfma_f32_32x32x16_bf16 v[34:49], v[146:149], v[98:101], v[34:49]
	v_mfma_f32_32x32x16_bf16 v[2:17], v[154:157], v[98:101], v[2:17]
	v_exp_f32_e32 v82, v82
	v_exp_f32_e32 v83, v83
	v_exp_f32_e32 v84, v84
	v_exp_f32_e32 v85, v85
	v_exp_f32_e32 v86, v86
	v_mfma_f32_32x32x16_bf16 v[34:49], v[150:153], v[102:105], v[34:49]
	v_exp_f32_e32 v87, v87
	v_exp_f32_e32 v88, v88
	v_exp_f32_e32 v89, v89
	v_exp_f32_e32 v90, v90
	v_exp_f32_e32 v91, v91
	v_mfma_f32_32x32x16_bf16 v[2:17], v[158:161], v[102:105], v[2:17]
	ds_read_b128 v[146:149], v198 offset:64
	ds_read_b128 v[150:153], v198 offset:96
	ds_read_b128 v[154:157], v197 offset:64
	ds_read_b128 v[158:161], v197 offset:96
	v_exp_f32_e32 v92, v92
	v_exp_f32_e32 v93, v93
	v_exp_f32_e32 v94, v94
	v_exp_f32_e32 v95, v95
	v_exp_f32_e32 v96, v96
	v_mfma_f32_32x32x16_bf16 v[98:113], v[238:241], v[130:133], v[18:33]
	v_exp_f32_e32 v97, v97
	v_add_f32_e32 v183, v82, v183
	v_add_f32_e32 v183, v83, v183
	v_add_f32_e32 v183, v84, v183
	v_add_f32_e32 v183, v85, v183
	v_mfma_f32_32x32x16_bf16 v[98:113], v[242:245], v[134:137], v[98:113]
	v_add_f32_e32 v183, v86, v183
	v_add_f32_e32 v183, v87, v183
	v_add_f32_e32 v183, v88, v183
	v_add_f32_e32 v183, v89, v183
	v_add_f32_e32 v183, v90, v183
	v_mfma_f32_32x32x16_bf16 v[98:113], v[246:249], v[138:141], v[98:113]
	v_add_f32_e32 v183, v91, v183
	v_add_f32_e32 v183, v92, v183
	v_add_f32_e32 v183, v93, v183
	v_add_f32_e32 v183, v94, v183
	v_add_f32_e32 v183, v95, v183
	v_mfma_f32_32x32x16_bf16 v[98:113], v[204:207], v[142:145], v[98:113]
	ds_read_b128 v[238:241], v199 offset:9216
	ds_read_b128 v[242:245], v199 offset:9248
	ds_read_b128 v[246:249], v199 offset:9280
	ds_read_b128 v[204:207], v199 offset:9312
	v_add_f32_e32 v183, v96, v183
	v_add_f32_e32 v183, v97, v183
	v_cvt_pk_bf16_f32 v82, v82, v83
	v_cvt_pk_bf16_f32 v83, v84, v85
	v_cvt_pk_bf16_f32 v84, v86, v87
	v_cvt_pk_bf16_f32 v85, v88, v89
	v_cvt_pk_bf16_f32 v86, v90, v91
	v_cvt_pk_bf16_f32 v87, v92, v93
	v_cvt_pk_bf16_f32 v88, v94, v95
	v_cvt_pk_bf16_f32 v89, v96, v97
	s_nop 0
	s_waitcnt lgkmcnt(4)
; __device__ __forceinline__ unsigned cvtpk(float lo, float hi) { f32x2_t v = {lo, hi}; bf16x2_t b = __builtin_convertvector(v, bf16x2_t); return __builtin_bit_cast(unsigned, b); }
; __device__ __forceinline__ bool attn_unit(const Ptrs& P, LAS unsigned char* lds, int unit, int tid, int wave, int lane, bool pre, int nxt) {
;     ...
;         for (int kt = 0; kt < 4; ++kt) {
;             if (c == 0 && 32 * kt + 31 < q0) continue;
;             if (c == 2 && 32 * kt > q0 + 63) continue;
;             bf16x8_t kf[4], vf[2][2];
; #pragma unroll
;             for (int ds = 0; ds < 4; ++ds) kf[ds] = *(const LAS bf16x8_t*)(Kl + (32 * kt + r) * AT_KP + (16 * ds + 8 * hh) * 2);
; #pragma unroll
;             for (int db = 0; db < 2; ++db)
; #pragma unroll
;                 for (int s = 0; s < 2; ++s) vf[db][s] = *(const LAS bf16x8_t*)(Vl + (32 * db + r) * AT_VP + (32 * kt + 16 * s + 8 * hh) * 2);
; #pragma unroll
;             for (int cb = 0; cb < 2; ++cb) {
;                 const int dq = 32 * kt - (q0 + 32 * cb);
;                 if ((c == 0 && dq < 0) || (c == 2 && dq > 0)) continue;
;                 const bool diag = (c == 0 || c == 2) && dq == 0;
;                 f32x16 st = MFMA32(kf[0], qf[cb][0], negm);
;                 st = MFMA32(kf[1], qf[cb][1], st); st = MFMA32(kf[2], qf[cb][2], st); st = MFMA32(kf[3], qf[cb][3], st);
;                 float p[16];
; #pragma unroll
;                 for (int i = 0; i < 16; ++i) p[i] = __builtin_amdgcn_exp2f(st[i]);
;                 if (diag) {
;                     const int thr = r - 4 * hh;
; #pragma unroll
;                     for (int i = 0; i < 16; ++i) { const bool vis = c == 0 ? crow(i, 0) >= thr : crow(i, 0) <= thr; p[i] = vis ? p[i] : 0.f; }
;                 }
;                 float s4 = 0.f;
; #pragma unroll
;                 for (int i = 0; i < 16; ++i) s4 += p[i];
;                 rs[cb] += s4;
; #pragma unroll
;                 for (int s = 0; s < 2; ++s) {
;                     u32x4 w; w.x = cvtpk(p[8 * s], p[8 * s + 1]); w.y = cvtpk(p[8 * s + 2], p[8 * s + 3]); w.z = cvtpk(p[8 * s + 4], p[8 * s + 5]); w.w = cvtpk(p[8 * s + 6], p[8 * s + 7]);
;                     const bf16x8_t pb = __builtin_bit_cast(bf16x8_t, w);
;                     o[0][cb] = MFMA32(vf[0][s], pb, o[0][cb]); o[1][cb] = MFMA32(vf[1][s], pb, o[1][cb]);
;                 }
;             }
;         }
	v_mfma_f32_32x32x16_bf16 v[66:81], v[146:149], v[82:85], v[66:81]
	v_mfma_f32_32x32x16_bf16 v[50:65], v[154:157], v[82:85], v[50:65]
	v_exp_f32_e32 v98, v98
	v_exp_f32_e32 v99, v99
	v_exp_f32_e32 v100, v100
	v_exp_f32_e32 v101, v101
	v_exp_f32_e32 v102, v102
	v_mfma_f32_32x32x16_bf16 v[66:81], v[150:153], v[86:89], v[66:81]
	v_exp_f32_e32 v103, v103
	v_exp_f32_e32 v104, v104
	v_exp_f32_e32 v105, v105
	v_exp_f32_e32 v106, v106
	v_exp_f32_e32 v107, v107
	v_mfma_f32_32x32x16_bf16 v[50:65], v[158:161], v[86:89], v[50:65]
	v_exp_f32_e32 v108, v108
	v_exp_f32_e32 v109, v109
	v_exp_f32_e32 v110, v110
	v_exp_f32_e32 v111, v111
	v_exp_f32_e32 v112, v112
	s_waitcnt lgkmcnt(0)
	v_mfma_f32_32x32x16_bf16 v[82:97], v[238:241], v[114:117], v[18:33]
	v_exp_f32_e32 v113, v113
	v_add_f32_e32 v182, v98, v182
	v_add_f32_e32 v182, v99, v182
	v_add_f32_e32 v182, v100, v182
	v_add_f32_e32 v182, v101, v182
	v_mfma_f32_32x32x16_bf16 v[82:97], v[242:245], v[118:121], v[82:97]
	v_add_f32_e32 v182, v102, v182
	v_add_f32_e32 v182, v103, v182
	v_add_f32_e32 v182, v104, v182
	v_add_f32_e32 v182, v105, v182
	v_add_f32_e32 v182, v106, v182
	v_mfma_f32_32x32x16_bf16 v[82:97], v[246:249], v[122:125], v[82:97]
	v_add_f32_e32 v182, v107, v182
	v_add_f32_e32 v182, v108, v182
	v_add_f32_e32 v182, v109, v182
	v_add_f32_e32 v182, v110, v182
	v_add_f32_e32 v182, v111, v182
	v_mfma_f32_32x32x16_bf16 v[82:97], v[204:207], v[126:129], v[82:97]
	v_add_f32_e32 v182, v112, v182
	v_add_f32_e32 v182, v113, v182
	v_cvt_pk_bf16_f32 v98, v98, v99
	v_cvt_pk_bf16_f32 v99, v100, v101
	v_cvt_pk_bf16_f32 v100, v102, v103
	v_cvt_pk_bf16_f32 v101, v104, v105
	v_cvt_pk_bf16_f32 v102, v106, v107
	v_cvt_pk_bf16_f32 v103, v108, v109
	v_cvt_pk_bf16_f32 v104, v110, v111
	v_cvt_pk_bf16_f32 v105, v112, v113
	s_nop 0
	v_mfma_f32_32x32x16_bf16 v[34:49], v[146:149], v[98:101], v[34:49]
	v_mfma_f32_32x32x16_bf16 v[2:17], v[154:157], v[98:101], v[2:17]
	v_exp_f32_e32 v82, v82
	v_exp_f32_e32 v83, v83
	v_exp_f32_e32 v84, v84
	v_exp_f32_e32 v85, v85
	v_exp_f32_e32 v86, v86
	v_mfma_f32_32x32x16_bf16 v[34:49], v[150:153], v[102:105], v[34:49]
	v_exp_f32_e32 v87, v87
	v_exp_f32_e32 v88, v88
	v_exp_f32_e32 v89, v89
	v_exp_f32_e32 v90, v90
	v_exp_f32_e32 v91, v91
	v_mfma_f32_32x32x16_bf16 v[2:17], v[158:161], v[102:105], v[2:17]
	ds_read_b128 v[146:149], v198 offset:128
	ds_read_b128 v[150:153], v198 offset:160
	ds_read_b128 v[154:157], v197 offset:128
	ds_read_b128 v[158:161], v197 offset:160
	v_exp_f32_e32 v92, v92
	v_exp_f32_e32 v93, v93
	v_exp_f32_e32 v94, v94
	v_exp_f32_e32 v95, v95
	v_exp_f32_e32 v96, v96
	v_mfma_f32_32x32x16_bf16 v[98:113], v[238:241], v[130:133], v[18:33]
	v_exp_f32_e32 v97, v97
	v_add_f32_e32 v183, v82, v183
	v_add_f32_e32 v183, v83, v183
	v_add_f32_e32 v183, v84, v183
	v_add_f32_e32 v183, v85, v183
	v_mfma_f32_32x32x16_bf16 v[98:113], v[242:245], v[134:137], v[98:113]
	v_add_f32_e32 v183, v86, v183
	v_add_f32_e32 v183, v87, v183
	v_add_f32_e32 v183, v88, v183
	v_add_f32_e32 v183, v89, v183
	v_add_f32_e32 v183, v90, v183
	v_mfma_f32_32x32x16_bf16 v[98:113], v[246:249], v[138:141], v[98:113]
	v_add_f32_e32 v183, v91, v183
	v_add_f32_e32 v183, v92, v183
	v_add_f32_e32 v183, v93, v183
	v_add_f32_e32 v183, v94, v183
	v_add_f32_e32 v183, v95, v183
	v_mfma_f32_32x32x16_bf16 v[98:113], v[204:207], v[142:145], v[98:113]
	ds_read_b128 v[238:241], v199 offset:13824
	ds_read_b128 v[242:245], v199 offset:13856
	ds_read_b128 v[246:249], v199 offset:13888
	ds_read_b128 v[204:207], v199 offset:13920
	v_add_f32_e32 v183, v96, v183
	v_add_f32_e32 v183, v97, v183
	v_cvt_pk_bf16_f32 v82, v82, v83
	v_cvt_pk_bf16_f32 v83, v84, v85
	v_cvt_pk_bf16_f32 v84, v86, v87
	v_cvt_pk_bf16_f32 v85, v88, v89
	v_cvt_pk_bf16_f32 v86, v90, v91
	v_cvt_pk_bf16_f32 v87, v92, v93
	v_cvt_pk_bf16_f32 v88, v94, v95
	v_cvt_pk_bf16_f32 v89, v96, v97
	s_nop 0
	s_waitcnt lgkmcnt(4)
	v_mfma_f32_32x32x16_bf16 v[66:81], v[146:149], v[82:85], v[66:81]
	v_mfma_f32_32x32x16_bf16 v[50:65], v[154:157], v[82:85], v[50:65]
	v_exp_f32_e32 v98, v98
	v_exp_f32_e32 v99, v99
	v_exp_f32_e32 v100, v100
	v_exp_f32_e32 v101, v101
	v_exp_f32_e32 v102, v102
	v_mfma_f32_32x32x16_bf16 v[66:81], v[150:153], v[86:89], v[66:81]
	v_exp_f32_e32 v103, v103
	v_exp_f32_e32 v104, v104
	v_exp_f32_e32 v105, v105
	v_exp_f32_e32 v106, v106
	v_exp_f32_e32 v107, v107
	v_mfma_f32_32x32x16_bf16 v[50:65], v[158:161], v[86:89], v[50:65]
	v_exp_f32_e32 v108, v108
	v_exp_f32_e32 v109, v109
	v_exp_f32_e32 v110, v110
	v_exp_f32_e32 v111, v111
	v_exp_f32_e32 v112, v112
	s_waitcnt lgkmcnt(0)
; __device__ __forceinline__ unsigned cvtpk(float lo, float hi) { f32x2_t v = {lo, hi}; bf16x2_t b = __builtin_convertvector(v, bf16x2_t); return __builtin_bit_cast(unsigned, b); }
; __device__ __forceinline__ bool attn_unit(const Ptrs& P, LAS unsigned char* lds, int unit, int tid, int wave, int lane, bool pre, int nxt) {
;     ...
;         for (int kt = 0; kt < 4; ++kt) {
;             if (c == 0 && 32 * kt + 31 < q0) continue;
;             if (c == 2 && 32 * kt > q0 + 63) continue;
;             bf16x8_t kf[4], vf[2][2];
; #pragma unroll
;             for (int ds = 0; ds < 4; ++ds) kf[ds] = *(const LAS bf16x8_t*)(Kl + (32 * kt + r) * AT_KP + (16 * ds + 8 * hh) * 2);
; #pragma unroll
;             for (int db = 0; db < 2; ++db)
; #pragma unroll
;                 for (int s = 0; s < 2; ++s) vf[db][s] = *(const LAS bf16x8_t*)(Vl + (32 * db + r) * AT_VP + (32 * kt + 16 * s + 8 * hh) * 2);
; #pragma unroll
;             for (int cb = 0; cb < 2; ++cb) {
;                 const int dq = 32 * kt - (q0 + 32 * cb);
;                 if ((c == 0 && dq < 0) || (c == 2 && dq > 0)) continue;
;                 const bool diag = (c == 0 || c == 2) && dq == 0;
;                 f32x16 st = MFMA32(kf[0], qf[cb][0], negm);
;                 st = MFMA32(kf[1], qf[cb][1], st); st = MFMA32(kf[2], qf[cb][2], st); st = MFMA32(kf[3], qf[cb][3], st);
;                 float p[16];
; #pragma unroll
;                 for (int i = 0; i < 16; ++i) p[i] = __builtin_amdgcn_exp2f(st[i]);
;                 if (diag) {
;                     const int thr = r - 4 * hh;
; #pragma unroll
;                     for (int i = 0; i < 16; ++i) { const bool vis = c == 0 ? crow(i, 0) >= thr : crow(i, 0) <= thr; p[i] = vis ? p[i] : 0.f; }
;                 }
;                 float s4 = 0.f;
; #pragma unroll
;                 for (int i = 0; i < 16; ++i) s4 += p[i];
;                 rs[cb] += s4;
; #pragma unroll
;                 for (int s = 0; s < 2; ++s) {
;                     u32x4 w; w.x = cvtpk(p[8 * s], p[8 * s + 1]); w.y = cvtpk(p[8 * s + 2], p[8 * s + 3]); w.z = cvtpk(p[8 * s + 4], p[8 * s + 5]); w.w = cvtpk(p[8 * s + 6], p[8 * s + 7]);
;                     const bf16x8_t pb = __builtin_bit_cast(bf16x8_t, w);
;                     o[0][cb] = MFMA32(vf[0][s], pb, o[0][cb]); o[1][cb] = MFMA32(vf[1][s], pb, o[1][cb]);
;                 }
;             }
;         }
;         AT_SYNC();
	v_mfma_f32_32x32x16_bf16 v[82:97], v[238:241], v[114:117], v[18:33]
	v_exp_f32_e32 v113, v113
	v_add_f32_e32 v182, v98, v182
	v_add_f32_e32 v182, v99, v182
	v_add_f32_e32 v182, v100, v182
	v_add_f32_e32 v182, v101, v182
	v_mfma_f32_32x32x16_bf16 v[82:97], v[242:245], v[118:121], v[82:97]
	v_add_f32_e32 v182, v102, v182
	v_add_f32_e32 v182, v103, v182
	v_add_f32_e32 v182, v104, v182
	v_add_f32_e32 v182, v105, v182
	v_add_f32_e32 v182, v106, v182
	v_mfma_f32_32x32x16_bf16 v[82:97], v[246:249], v[122:125], v[82:97]
	v_add_f32_e32 v182, v107, v182
	v_add_f32_e32 v182, v108, v182
	v_add_f32_e32 v182, v109, v182
	v_add_f32_e32 v182, v110, v182
	v_add_f32_e32 v182, v111, v182
	v_mfma_f32_32x32x16_bf16 v[82:97], v[204:207], v[126:129], v[82:97]
	v_add_f32_e32 v182, v112, v182
	v_add_f32_e32 v182, v113, v182
	v_cvt_pk_bf16_f32 v98, v98, v99
	v_cvt_pk_bf16_f32 v99, v100, v101
	v_cvt_pk_bf16_f32 v100, v102, v103
	v_cvt_pk_bf16_f32 v101, v104, v105
	v_cvt_pk_bf16_f32 v102, v106, v107
	v_cvt_pk_bf16_f32 v103, v108, v109
	v_cvt_pk_bf16_f32 v104, v110, v111
	v_cvt_pk_bf16_f32 v105, v112, v113
	s_nop 0
	v_mfma_f32_32x32x16_bf16 v[34:49], v[146:149], v[98:101], v[34:49]
	v_mfma_f32_32x32x16_bf16 v[2:17], v[154:157], v[98:101], v[2:17]
	v_exp_f32_e32 v82, v82
	v_exp_f32_e32 v83, v83
	v_exp_f32_e32 v84, v84
	v_exp_f32_e32 v85, v85
	v_exp_f32_e32 v86, v86
	v_mfma_f32_32x32x16_bf16 v[34:49], v[150:153], v[102:105], v[34:49]
	v_exp_f32_e32 v87, v87
	v_exp_f32_e32 v88, v88
	v_exp_f32_e32 v89, v89
	v_exp_f32_e32 v90, v90
	v_exp_f32_e32 v91, v91
	v_mfma_f32_32x32x16_bf16 v[2:17], v[158:161], v[102:105], v[2:17]
	ds_read_b128 v[146:149], v198 offset:192
	ds_read_b128 v[150:153], v198 offset:224
	ds_read_b128 v[154:157], v197 offset:192
	ds_read_b128 v[158:161], v197 offset:224
	v_exp_f32_e32 v92, v92
	v_exp_f32_e32 v93, v93
	v_exp_f32_e32 v94, v94
	v_exp_f32_e32 v95, v95
	v_exp_f32_e32 v96, v96
	v_mfma_f32_32x32x16_bf16 v[98:113], v[238:241], v[130:133], v[18:33]
	v_exp_f32_e32 v97, v97
	v_add_f32_e32 v183, v82, v183
	v_add_f32_e32 v183, v83, v183
	v_add_f32_e32 v183, v84, v183
	v_add_f32_e32 v183, v85, v183
	v_mfma_f32_32x32x16_bf16 v[98:113], v[242:245], v[134:137], v[98:113]
	v_add_f32_e32 v183, v86, v183
	v_add_f32_e32 v183, v87, v183
	v_add_f32_e32 v183, v88, v183
	v_add_f32_e32 v183, v89, v183
	v_add_f32_e32 v183, v90, v183
	v_mfma_f32_32x32x16_bf16 v[98:113], v[246:249], v[138:141], v[98:113]
	v_add_f32_e32 v183, v91, v183
	v_add_f32_e32 v183, v92, v183
	v_add_f32_e32 v183, v93, v183
	v_add_f32_e32 v183, v94, v183
	v_add_f32_e32 v183, v95, v183
	v_mfma_f32_32x32x16_bf16 v[98:113], v[204:207], v[142:145], v[98:113]
	v_add_f32_e32 v183, v96, v183
	v_add_f32_e32 v183, v97, v183
	v_cvt_pk_bf16_f32 v82, v82, v83
	v_cvt_pk_bf16_f32 v83, v84, v85
	v_cvt_pk_bf16_f32 v84, v86, v87
	v_cvt_pk_bf16_f32 v85, v88, v89
	v_cvt_pk_bf16_f32 v86, v90, v91
	v_cvt_pk_bf16_f32 v87, v92, v93
	v_cvt_pk_bf16_f32 v88, v94, v95
	v_cvt_pk_bf16_f32 v89, v96, v97
	s_nop 0
	s_waitcnt lgkmcnt(0)
	v_mfma_f32_32x32x16_bf16 v[66:81], v[146:149], v[82:85], v[66:81]
	v_mfma_f32_32x32x16_bf16 v[50:65], v[154:157], v[82:85], v[50:65]
	v_exp_f32_e32 v98, v98
	v_exp_f32_e32 v99, v99
	v_exp_f32_e32 v100, v100
	v_exp_f32_e32 v101, v101
	v_exp_f32_e32 v102, v102
	v_mfma_f32_32x32x16_bf16 v[66:81], v[150:153], v[86:89], v[66:81]
	v_exp_f32_e32 v103, v103
	v_exp_f32_e32 v104, v104
	v_exp_f32_e32 v105, v105
	v_exp_f32_e32 v106, v106
	v_exp_f32_e32 v107, v107
	v_mfma_f32_32x32x16_bf16 v[50:65], v[158:161], v[86:89], v[50:65]
	v_exp_f32_e32 v108, v108
	v_exp_f32_e32 v109, v109
	v_exp_f32_e32 v110, v110
	v_exp_f32_e32 v111, v111
	v_exp_f32_e32 v112, v112
	v_exp_f32_e32 v113, v113
	v_add_f32_e32 v182, v98, v182
	v_add_f32_e32 v182, v99, v182
	v_add_f32_e32 v182, v100, v182
	v_add_f32_e32 v182, v101, v182
	v_add_f32_e32 v182, v102, v182
	v_add_f32_e32 v182, v103, v182
	v_add_f32_e32 v182, v104, v182
	v_add_f32_e32 v182, v105, v182
	v_add_f32_e32 v182, v106, v182
	v_add_f32_e32 v182, v107, v182
	v_add_f32_e32 v182, v108, v182
	v_add_f32_e32 v182, v109, v182
	v_add_f32_e32 v182, v110, v182
	v_add_f32_e32 v182, v111, v182
	v_add_f32_e32 v182, v112, v182
	v_add_f32_e32 v182, v113, v182
	v_cvt_pk_bf16_f32 v98, v98, v99
	v_cvt_pk_bf16_f32 v99, v100, v101
	v_cvt_pk_bf16_f32 v100, v102, v103
	v_cvt_pk_bf16_f32 v101, v104, v105
	v_cvt_pk_bf16_f32 v102, v106, v107
	v_cvt_pk_bf16_f32 v103, v108, v109
	v_cvt_pk_bf16_f32 v104, v110, v111
	v_cvt_pk_bf16_f32 v105, v112, v113
	s_nop 1
	v_mfma_f32_32x32x16_bf16 v[34:49], v[146:149], v[98:101], v[34:49]
	v_mfma_f32_32x32x16_bf16 v[2:17], v[154:157], v[98:101], v[2:17]
	v_mfma_f32_32x32x16_bf16 v[34:49], v[150:153], v[102:105], v[34:49]
	v_mfma_f32_32x32x16_bf16 v[2:17], v[158:161], v[102:105], v[2:17]
	s_movk_i32 s43, 0x100
	s_waitcnt vmcnt(0) lgkmcnt(0)
	s_barrier
	s_andn2_b64 vcc, exec, s[70:71]
	s_cbranch_vccnz .LBB9_391
	s_and_b64 vcc, exec, s[68:69]
	v_mov_b32_e32 v83, v193
	v_mov_b32_e32 v82, v192
	s_mov_b32 s43, s50
	s_cbranch_vccz .LBB9_376

; #define LAS __attribute__((address_space(3)))
; __device__ __forceinline__ bool attn_unit(const Ptrs& P, LAS unsigned char* lds, int unit, int tid, int wave, int lane, bool pre, int nxt) {
;     ...
;         const LAS unsigned char* Kl = lds + (c % 3) * AT_BUF; const LAS unsigned char* Vl = Kl + AT_KB;
; #pragma unroll 1
;         for (int kt = 0; kt < 4; ++kt) {
;             if (c == 0 && 32 * kt + 31 < q0) continue;
;             if (c == 2 && 32 * kt > q0 + 63) continue;
;             bf16x8_t kf[4], vf[2][2];
; #pragma unroll
;             for (int ds = 0; ds < 4; ++ds) kf[ds] = *(const LAS bf16x8_t*)(Kl + (32 * kt + r) * AT_KP + (16 * ds + 8 * hh) * 2);
; #pragma unroll
;             for (int db = 0; db < 2; ++db)
; #pragma unroll
;                 for (int s = 0; s < 2; ++s) vf[db][s] = *(const LAS bf16x8_t*)(Vl + (32 * db + r) * AT_VP + (32 * kt + 16 * s + 8 * hh) * 2);
; #pragma unroll
;             for (int cb = 0; cb < 2; ++cb) {
;                 const int dq = 32 * kt - (q0 + 32 * cb);
;                 if ((c == 0 && dq < 0) || (c == 2 && dq > 0)) continue;
;                 const bool diag = (c == 0 || c == 2) && dq == 0;
;                 f32x16 st = MFMA32(kf[0], qf[cb][0], negm);
;                 st = MFMA32(kf[1], qf[cb][1], st); st = MFMA32(kf[2], qf[cb][2], st); st = MFMA32(kf[3], qf[cb][3], st);
;                 float p[16];
; #pragma unroll
;                 for (int i = 0; i < 16; ++i) p[i] = __builtin_amdgcn_exp2f(st[i]);
;                 if (diag) {
;                     const int thr = r - 4 * hh;
; #pragma unroll
;                     for (int i = 0; i < 16; ++i) { const bool vis = c == 0 ? crow(i, 0) >= thr : crow(i, 0) <= thr; p[i] = vis ? p[i] : 0.f; }
;                 }
;                 float s4 = 0.f;
; #pragma unroll
;                 for (int i = 0; i < 16; ++i) s4 += p[i];
;                 rs[cb] += s4;
; #pragma unroll
;                 for (int s = 0; s < 2; ++s) {
;                     u32x4 w; w.x = cvtpk(p[8 * s], p[8 * s + 1]); w.y = cvtpk(p[8 * s + 2], p[8 * s + 3]); w.z = cvtpk(p[8 * s + 4], p[8 * s + 5]); w.w = cvtpk(p[8 * s + 6], p[8 * s + 7]);
;                     const bf16x8_t pb = __builtin_bit_cast(bf16x8_t, w);
;                     o[0][cb] = MFMA32(vf[0][s], pb, o[0][cb]); o[1][cb] = MFMA32(vf[1][s], pb, o[1][cb]);
;                 }
;             }
;         }
.LBB9_400:
	ds_read_b128 v[238:241], v196 offset:0
	ds_read_b128 v[242:245], v196 offset:32
	ds_read_b128 v[246:249], v196 offset:64
	ds_read_b128 v[204:207], v196 offset:96
	s_waitcnt lgkmcnt(0)
	v_mfma_f32_32x32x16_bf16 v[82:97], v[238:241], v[114:117], v[18:33]
	v_mfma_f32_32x32x16_bf16 v[82:97], v[242:245], v[118:121], v[82:97]
	v_mfma_f32_32x32x16_bf16 v[82:97], v[246:249], v[122:125], v[82:97]
	v_mfma_f32_32x32x16_bf16 v[82:97], v[204:207], v[126:129], v[82:97]
	v_mfma_f32_32x32x16_bf16 v[98:113], v[238:241], v[130:133], v[18:33]
	v_mfma_f32_32x32x16_bf16 v[98:113], v[242:245], v[134:137], v[98:113]
	v_mfma_f32_32x32x16_bf16 v[98:113], v[246:249], v[138:141], v[98:113]
	v_mfma_f32_32x32x16_bf16 v[98:113], v[204:207], v[142:145], v[98:113]
	ds_read_b128 v[146:149], v195 offset:0
	ds_read_b128 v[150:153], v195 offset:32
	ds_read_b128 v[154:157], v194 offset:0
	ds_read_b128 v[158:161], v194 offset:32
	ds_read_b128 v[238:241], v196 offset:4608
	ds_read_b128 v[242:245], v196 offset:4640
	ds_read_b128 v[246:249], v196 offset:4672
	ds_read_b128 v[204:207], v196 offset:4704
	v_exp_f32_e32 v82, v82
	v_exp_f32_e32 v83, v83
	v_exp_f32_e32 v84, v84
	v_exp_f32_e32 v85, v85
	v_exp_f32_e32 v86, v86
	v_exp_f32_e32 v87, v87
	v_exp_f32_e32 v88, v88
	v_exp_f32_e32 v89, v89
	v_exp_f32_e32 v90, v90
	v_exp_f32_e32 v91, v91
	v_exp_f32_e32 v92, v92
	v_exp_f32_e32 v93, v93
	v_exp_f32_e32 v94, v94
	v_exp_f32_e32 v95, v95
	v_exp_f32_e32 v96, v96
	v_exp_f32_e32 v97, v97
	v_add_f32_e32 v183, v82, v183
	v_add_f32_e32 v183, v83, v183
	v_add_f32_e32 v183, v84, v183
	v_add_f32_e32 v183, v85, v183
	v_add_f32_e32 v183, v86, v183
	v_add_f32_e32 v183, v87, v183
	v_add_f32_e32 v183, v88, v183
	v_add_f32_e32 v183, v89, v183
	v_add_f32_e32 v183, v90, v183
	v_add_f32_e32 v183, v91, v183
	v_add_f32_e32 v183, v92, v183
	v_add_f32_e32 v183, v93, v183
	v_add_f32_e32 v183, v94, v183
	v_add_f32_e32 v183, v95, v183
	v_add_f32_e32 v183, v96, v183
	v_add_f32_e32 v183, v97, v183
	v_cvt_pk_bf16_f32 v82, v82, v83
	v_cvt_pk_bf16_f32 v83, v84, v85
	v_cvt_pk_bf16_f32 v84, v86, v87
	v_cvt_pk_bf16_f32 v85, v88, v89
	v_cvt_pk_bf16_f32 v86, v90, v91
	v_cvt_pk_bf16_f32 v87, v92, v93
	v_cvt_pk_bf16_f32 v88, v94, v95
	v_cvt_pk_bf16_f32 v89, v96, v97
	s_nop 0
	s_waitcnt lgkmcnt(4)
	v_mfma_f32_32x32x16_bf16 v[66:81], v[146:149], v[82:85], v[66:81]
	v_mfma_f32_32x32x16_bf16 v[50:65], v[154:157], v[82:85], v[50:65]
	v_exp_f32_e32 v98, v98
	v_exp_f32_e32 v99, v99
	v_exp_f32_e32 v100, v100
	v_exp_f32_e32 v101, v101
	v_exp_f32_e32 v102, v102
	v_mfma_f32_32x32x16_bf16 v[66:81], v[150:153], v[86:89], v[66:81]
	v_exp_f32_e32 v103, v103
	v_exp_f32_e32 v104, v104
	v_exp_f32_e32 v105, v105
	v_exp_f32_e32 v106, v106
	v_exp_f32_e32 v107, v107
	v_mfma_f32_32x32x16_bf16 v[50:65], v[158:161], v[86:89], v[50:65]
	v_exp_f32_e32 v108, v108
	v_exp_f32_e32 v109, v109
	v_exp_f32_e32 v110, v110
	v_exp_f32_e32 v111, v111
	v_exp_f32_e32 v112, v112
	s_waitcnt lgkmcnt(0)
	v_mfma_f32_32x32x16_bf16 v[82:97], v[238:241], v[114:117], v[18:33]
	v_exp_f32_e32 v113, v113
	v_add_f32_e32 v182, v98, v182
	v_add_f32_e32 v182, v99, v182
	v_add_f32_e32 v182, v100, v182
	v_add_f32_e32 v182, v101, v182
	v_mfma_f32_32x32x16_bf16 v[82:97], v[242:245], v[118:121], v[82:97]
	v_add_f32_e32 v182, v102, v182
	v_add_f32_e32 v182, v103, v182
	v_add_f32_e32 v182, v104, v182
	v_add_f32_e32 v182, v105, v182
	v_add_f32_e32 v182, v106, v182
	v_mfma_f32_32x32x16_bf16 v[82:97], v[246:249], v[122:125], v[82:97]
	v_add_f32_e32 v182, v107, v182
	v_add_f32_e32 v182, v108, v182
	v_add_f32_e32 v182, v109, v182
	v_add_f32_e32 v182, v110, v182
	v_add_f32_e32 v182, v111, v182
	v_mfma_f32_32x32x16_bf16 v[82:97], v[204:207], v[126:129], v[82:97]
	v_add_f32_e32 v182, v112, v182
	v_add_f32_e32 v182, v113, v182
	v_cvt_pk_bf16_f32 v98, v98, v99
	v_cvt_pk_bf16_f32 v99, v100, v101
	v_cvt_pk_bf16_f32 v100, v102, v103
	v_cvt_pk_bf16_f32 v101, v104, v105
	v_cvt_pk_bf16_f32 v102, v106, v107
	v_cvt_pk_bf16_f32 v103, v108, v109
	v_cvt_pk_bf16_f32 v104, v110, v111
	v_cvt_pk_bf16_f32 v105, v112, v113
	s_nop 0
	v_mfma_f32_32x32x16_bf16 v[34:49], v[146:149], v[98:101], v[34:49]
	v_mfma_f32_32x32x16_bf16 v[2:17], v[154:157], v[98:101], v[2:17]
	v_exp_f32_e32 v82, v82
	v_exp_f32_e32 v83, v83
	v_exp_f32_e32 v84, v84
	v_exp_f32_e32 v85, v85
	v_exp_f32_e32 v86, v86
	v_mfma_f32_32x32x16_bf16 v[34:49], v[150:153], v[102:105], v[34:49]
	v_exp_f32_e32 v87, v87
	v_exp_f32_e32 v88, v88
	v_exp_f32_e32 v89, v89
	v_exp_f32_e32 v90, v90
	v_exp_f32_e32 v91, v91
	v_mfma_f32_32x32x16_bf16 v[2:17], v[158:161], v[102:105], v[2:17]
	ds_read_b128 v[146:149], v195 offset:64
	ds_read_b128 v[150:153], v195 offset:96
	ds_read_b128 v[154:157], v194 offset:64
	ds_read_b128 v[158:161], v194 offset:96
	v_exp_f32_e32 v92, v92
	v_exp_f32_e32 v93, v93
	v_exp_f32_e32 v94, v94
	v_exp_f32_e32 v95, v95
	v_exp_f32_e32 v96, v96
	v_mfma_f32_32x32x16_bf16 v[98:113], v[238:241], v[130:133], v[18:33]
	v_exp_f32_e32 v97, v97
	v_add_f32_e32 v183, v82, v183
	v_add_f32_e32 v183, v83, v183
	v_add_f32_e32 v183, v84, v183
	v_add_f32_e32 v183, v85, v183
	v_mfma_f32_32x32x16_bf16 v[98:113], v[242:245], v[134:137], v[98:113]
	v_add_f32_e32 v183, v86, v183
	v_add_f32_e32 v183, v87, v183
	v_add_f32_e32 v183, v88, v183
	v_add_f32_e32 v183, v89, v183
	v_add_f32_e32 v183, v90, v183
	v_mfma_f32_32x32x16_bf16 v[98:113], v[246:249], v[138:141], v[98:113]
	v_add_f32_e32 v183, v91, v183
	v_add_f32_e32 v183, v92, v183
	v_add_f32_e32 v183, v93, v183
	v_add_f32_e32 v183, v94, v183
	v_add_f32_e32 v183, v95, v183
	v_mfma_f32_32x32x16_bf16 v[98:113], v[204:207], v[142:145], v[98:113]
	ds_read_b128 v[238:241], v196 offset:9216
	ds_read_b128 v[242:245], v196 offset:9248
	ds_read_b128 v[246:249], v196 offset:9280
	ds_read_b128 v[204:207], v196 offset:9312
	v_add_f32_e32 v183, v96, v183
	v_add_f32_e32 v183, v97, v183
	v_cvt_pk_bf16_f32 v82, v82, v83
	v_cvt_pk_bf16_f32 v83, v84, v85
	v_cvt_pk_bf16_f32 v84, v86, v87
	v_cvt_pk_bf16_f32 v85, v88, v89
	v_cvt_pk_bf16_f32 v86, v90, v91
	v_cvt_pk_bf16_f32 v87, v92, v93
	v_cvt_pk_bf16_f32 v88, v94, v95
	v_cvt_pk_bf16_f32 v89, v96, v97
	s_nop 0
	s_waitcnt lgkmcnt(4)
; __device__ __forceinline__ unsigned cvtpk(float lo, float hi) { f32x2_t v = {lo, hi}; bf16x2_t b = __builtin_convertvector(v, bf16x2_t); return __builtin_bit_cast(unsigned, b); }
; __device__ __forceinline__ bool attn_unit(const Ptrs& P, LAS unsigned char* lds, int unit, int tid, int wave, int lane, bool pre, int nxt) {
;     ...
;         for (int kt = 0; kt < 4; ++kt) {
;             if (c == 0 && 32 * kt + 31 < q0) continue;
;             if (c == 2 && 32 * kt > q0 + 63) continue;
;             bf16x8_t kf[4], vf[2][2];
; #pragma unroll
;             for (int ds = 0; ds < 4; ++ds) kf[ds] = *(const LAS bf16x8_t*)(Kl + (32 * kt + r) * AT_KP + (16 * ds + 8 * hh) * 2);
; #pragma unroll
;             for (int db = 0; db < 2; ++db)
; #pragma unroll
;                 for (int s = 0; s < 2; ++s) vf[db][s] = *(const LAS bf16x8_t*)(Vl + (32 * db + r) * AT_VP + (32 * kt + 16 * s + 8 * hh) * 2);
; #pragma unroll
;             for (int cb = 0; cb < 2; ++cb) {
;                 const int dq = 32 * kt - (q0 + 32 * cb);
;                 if ((c == 0 && dq < 0) || (c == 2 && dq > 0)) continue;
;                 const bool diag = (c == 0 || c == 2) && dq == 0;
;                 f32x16 st = MFMA32(kf[0], qf[cb][0], negm);
;                 st = MFMA32(kf[1], qf[cb][1], st); st = MFMA32(kf[2], qf[cb][2], st); st = MFMA32(kf[3], qf[cb][3], st);
;                 float p[16];
; #pragma unroll
;                 for (int i = 0; i < 16; ++i) p[i] = __builtin_amdgcn_exp2f(st[i]);
;                 if (diag) {
;                     const int thr = r - 4 * hh;
; #pragma unroll
;                     for (int i = 0; i < 16; ++i) { const bool vis = c == 0 ? crow(i, 0) >= thr : crow(i, 0) <= thr; p[i] = vis ? p[i] : 0.f; }
;                 }
;                 float s4 = 0.f;
; #pragma unroll
;                 for (int i = 0; i < 16; ++i) s4 += p[i];
;                 rs[cb] += s4;
; #pragma unroll
;                 for (int s = 0; s < 2; ++s) {
;                     u32x4 w; w.x = cvtpk(p[8 * s], p[8 * s + 1]); w.y = cvtpk(p[8 * s + 2], p[8 * s + 3]); w.z = cvtpk(p[8 * s + 4], p[8 * s + 5]); w.w = cvtpk(p[8 * s + 6], p[8 * s + 7]);
;                     const bf16x8_t pb = __builtin_bit_cast(bf16x8_t, w);
;                     o[0][cb] = MFMA32(vf[0][s], pb, o[0][cb]); o[1][cb] = MFMA32(vf[1][s], pb, o[1][cb]);
;                 }
;             }
;         }
	v_mfma_f32_32x32x16_bf16 v[66:81], v[146:149], v[82:85], v[66:81]
	v_mfma_f32_32x32x16_bf16 v[50:65], v[154:157], v[82:85], v[50:65]
	v_exp_f32_e32 v98, v98
	v_exp_f32_e32 v99, v99
	v_exp_f32_e32 v100, v100
	v_exp_f32_e32 v101, v101
	v_exp_f32_e32 v102, v102
	v_mfma_f32_32x32x16_bf16 v[66:81], v[150:153], v[86:89], v[66:81]
	v_exp_f32_e32 v103, v103
	v_exp_f32_e32 v104, v104
	v_exp_f32_e32 v105, v105
	v_exp_f32_e32 v106, v106
	v_exp_f32_e32 v107, v107
	v_mfma_f32_32x32x16_bf16 v[50:65], v[158:161], v[86:89], v[50:65]
	v_exp_f32_e32 v108, v108
	v_exp_f32_e32 v109, v109
	v_exp_f32_e32 v110, v110
	v_exp_f32_e32 v111, v111
	v_exp_f32_e32 v112, v112
	s_waitcnt lgkmcnt(0)
	v_mfma_f32_32x32x16_bf16 v[82:97], v[238:241], v[114:117], v[18:33]
	v_exp_f32_e32 v113, v113
	v_add_f32_e32 v182, v98, v182
	v_add_f32_e32 v182, v99, v182
	v_add_f32_e32 v182, v100, v182
	v_add_f32_e32 v182, v101, v182
	v_mfma_f32_32x32x16_bf16 v[82:97], v[242:245], v[118:121], v[82:97]
	v_add_f32_e32 v182, v102, v182
	v_add_f32_e32 v182, v103, v182
	v_add_f32_e32 v182, v104, v182
	v_add_f32_e32 v182, v105, v182
	v_add_f32_e32 v182, v106, v182
	v_mfma_f32_32x32x16_bf16 v[82:97], v[246:249], v[122:125], v[82:97]
	v_add_f32_e32 v182, v107, v182
	v_add_f32_e32 v182, v108, v182
	v_add_f32_e32 v182, v109, v182
	v_add_f32_e32 v182, v110, v182
	v_add_f32_e32 v182, v111, v182
	v_mfma_f32_32x32x16_bf16 v[82:97], v[204:207], v[126:129], v[82:97]
	v_add_f32_e32 v182, v112, v182
	v_add_f32_e32 v182, v113, v182
	v_cvt_pk_bf16_f32 v98, v98, v99
	v_cvt_pk_bf16_f32 v99, v100, v101
	v_cvt_pk_bf16_f32 v100, v102, v103
	v_cvt_pk_bf16_f32 v101, v104, v105
	v_cvt_pk_bf16_f32 v102, v106, v107
	v_cvt_pk_bf16_f32 v103, v108, v109
	v_cvt_pk_bf16_f32 v104, v110, v111
	v_cvt_pk_bf16_f32 v105, v112, v113
	s_nop 0
	v_mfma_f32_32x32x16_bf16 v[34:49], v[146:149], v[98:101], v[34:49]
	v_mfma_f32_32x32x16_bf16 v[2:17], v[154:157], v[98:101], v[2:17]
	v_exp_f32_e32 v82, v82
	v_exp_f32_e32 v83, v83
	v_exp_f32_e32 v84, v84
	v_exp_f32_e32 v85, v85
	v_exp_f32_e32 v86, v86
	v_mfma_f32_32x32x16_bf16 v[34:49], v[150:153], v[102:105], v[34:49]
	v_exp_f32_e32 v87, v87
	v_exp_f32_e32 v88, v88
	v_exp_f32_e32 v89, v89
	v_exp_f32_e32 v90, v90
	v_exp_f32_e32 v91, v91
	v_mfma_f32_32x32x16_bf16 v[2:17], v[158:161], v[102:105], v[2:17]
	ds_read_b128 v[146:149], v195 offset:128
	ds_read_b128 v[150:153], v195 offset:160
	ds_read_b128 v[154:157], v194 offset:128
	ds_read_b128 v[158:161], v194 offset:160
	v_exp_f32_e32 v92, v92
	v_exp_f32_e32 v93, v93
	v_exp_f32_e32 v94, v94
	v_exp_f32_e32 v95, v95
	v_exp_f32_e32 v96, v96
	v_mfma_f32_32x32x16_bf16 v[98:113], v[238:241], v[130:133], v[18:33]
	v_exp_f32_e32 v97, v97
	v_add_f32_e32 v183, v82, v183
	v_add_f32_e32 v183, v83, v183
	v_add_f32_e32 v183, v84, v183
	v_add_f32_e32 v183, v85, v183
	v_mfma_f32_32x32x16_bf16 v[98:113], v[242:245], v[134:137], v[98:113]
	v_add_f32_e32 v183, v86, v183
	v_add_f32_e32 v183, v87, v183
	v_add_f32_e32 v183, v88, v183
	v_add_f32_e32 v183, v89, v183
	v_add_f32_e32 v183, v90, v183
	v_mfma_f32_32x32x16_bf16 v[98:113], v[246:249], v[138:141], v[98:113]
	v_add_f32_e32 v183, v91, v183
	v_add_f32_e32 v183, v92, v183
	v_add_f32_e32 v183, v93, v183
	v_add_f32_e32 v183, v94, v183
	v_add_f32_e32 v183, v95, v183
	v_mfma_f32_32x32x16_bf16 v[98:113], v[204:207], v[142:145], v[98:113]
	ds_read_b128 v[238:241], v196 offset:13824
	ds_read_b128 v[242:245], v196 offset:13856
	ds_read_b128 v[246:249], v196 offset:13888
	ds_read_b128 v[204:207], v196 offset:13920
	v_add_f32_e32 v183, v96, v183
	v_add_f32_e32 v183, v97, v183
	v_cvt_pk_bf16_f32 v82, v82, v83
	v_cvt_pk_bf16_f32 v83, v84, v85
	v_cvt_pk_bf16_f32 v84, v86, v87
	v_cvt_pk_bf16_f32 v85, v88, v89
	v_cvt_pk_bf16_f32 v86, v90, v91
	v_cvt_pk_bf16_f32 v87, v92, v93
	v_cvt_pk_bf16_f32 v88, v94, v95
	v_cvt_pk_bf16_f32 v89, v96, v97
	s_nop 0
	s_waitcnt lgkmcnt(4)
	v_mfma_f32_32x32x16_bf16 v[66:81], v[146:149], v[82:85], v[66:81]
	v_mfma_f32_32x32x16_bf16 v[50:65], v[154:157], v[82:85], v[50:65]
	v_exp_f32_e32 v98, v98
	v_exp_f32_e32 v99, v99
	v_exp_f32_e32 v100, v100
	v_exp_f32_e32 v101, v101
	v_exp_f32_e32 v102, v102
	v_mfma_f32_32x32x16_bf16 v[66:81], v[150:153], v[86:89], v[66:81]
	v_exp_f32_e32 v103, v103
	v_exp_f32_e32 v104, v104
	v_exp_f32_e32 v105, v105
	v_exp_f32_e32 v106, v106
	v_exp_f32_e32 v107, v107
	v_mfma_f32_32x32x16_bf16 v[50:65], v[158:161], v[86:89], v[50:65]
	v_exp_f32_e32 v108, v108
	v_exp_f32_e32 v109, v109
	v_exp_f32_e32 v110, v110
	v_exp_f32_e32 v111, v111
	v_exp_f32_e32 v112, v112
	s_waitcnt lgkmcnt(0)
; #define LAS __attribute__((address_space(3)))
; __device__ __forceinline__ bool attn_unit(const Ptrs& P, LAS unsigned char* lds, int unit, int tid, int wave, int lane, bool pre, int nxt) {
;     ...
;     const int n2 = nxt & 31; const bool pf = nxt >= 0 && n2 != 0;
;     ...
;         for (int kt = 0; kt < 4; ++kt) {
;             if (c == 0 && 32 * kt + 31 < q0) continue;
;             if (c == 2 && 32 * kt > q0 + 63) continue;
;             bf16x8_t kf[4], vf[2][2];
; #pragma unroll
;             for (int ds = 0; ds < 4; ++ds) kf[ds] = *(const LAS bf16x8_t*)(Kl + (32 * kt + r) * AT_KP + (16 * ds + 8 * hh) * 2);
; #pragma unroll
;             for (int db = 0; db < 2; ++db)
; #pragma unroll
;                 for (int s = 0; s < 2; ++s) vf[db][s] = *(const LAS bf16x8_t*)(Vl + (32 * db + r) * AT_VP + (32 * kt + 16 * s + 8 * hh) * 2);
; #pragma unroll
;             for (int cb = 0; cb < 2; ++cb) {
;                 const int dq = 32 * kt - (q0 + 32 * cb);
;                 if ((c == 0 && dq < 0) || (c == 2 && dq > 0)) continue;
;                 const bool diag = (c == 0 || c == 2) && dq == 0;
;                 f32x16 st = MFMA32(kf[0], qf[cb][0], negm);
;                 st = MFMA32(kf[1], qf[cb][1], st); st = MFMA32(kf[2], qf[cb][2], st); st = MFMA32(kf[3], qf[cb][3], st);
;                 float p[16];
; #pragma unroll
;                 for (int i = 0; i < 16; ++i) p[i] = __builtin_amdgcn_exp2f(st[i]);
;                 if (diag) {
;                     const int thr = r - 4 * hh;
; #pragma unroll
;                     for (int i = 0; i < 16; ++i) { const bool vis = c == 0 ? crow(i, 0) >= thr : crow(i, 0) <= thr; p[i] = vis ? p[i] : 0.f; }
;                 }
;                 float s4 = 0.f;
; #pragma unroll
;                 for (int i = 0; i < 16; ++i) s4 += p[i];
;                 rs[cb] += s4;
; #pragma unroll
;                 for (int s = 0; s < 2; ++s) {
;                     u32x4 w; w.x = cvtpk(p[8 * s], p[8 * s + 1]); w.y = cvtpk(p[8 * s + 2], p[8 * s + 3]); w.z = cvtpk(p[8 * s + 4], p[8 * s + 5]); w.w = cvtpk(p[8 * s + 6], p[8 * s + 7]);
;                     const bf16x8_t pb = __builtin_bit_cast(bf16x8_t, w);
;                     o[0][cb] = MFMA32(vf[0][s], pb, o[0][cb]); o[1][cb] = MFMA32(vf[1][s], pb, o[1][cb]);
;                 }
;             }
;         }
;         AT_SYNC();
	v_mfma_f32_32x32x16_bf16 v[82:97], v[238:241], v[114:117], v[18:33]
	v_exp_f32_e32 v113, v113
	v_add_f32_e32 v182, v98, v182
	v_add_f32_e32 v182, v99, v182
	v_add_f32_e32 v182, v100, v182
	v_add_f32_e32 v182, v101, v182
	v_mfma_f32_32x32x16_bf16 v[82:97], v[242:245], v[118:121], v[82:97]
	v_add_f32_e32 v182, v102, v182
	v_add_f32_e32 v182, v103, v182
	v_add_f32_e32 v182, v104, v182
	v_add_f32_e32 v182, v105, v182
	v_add_f32_e32 v182, v106, v182
	v_mfma_f32_32x32x16_bf16 v[82:97], v[246:249], v[122:125], v[82:97]
	v_add_f32_e32 v182, v107, v182
	v_add_f32_e32 v182, v108, v182
	v_add_f32_e32 v182, v109, v182
	v_add_f32_e32 v182, v110, v182
	v_add_f32_e32 v182, v111, v182
	v_mfma_f32_32x32x16_bf16 v[82:97], v[204:207], v[126:129], v[82:97]
	v_add_f32_e32 v182, v112, v182
	v_add_f32_e32 v182, v113, v182
	v_cvt_pk_bf16_f32 v98, v98, v99
	v_cvt_pk_bf16_f32 v99, v100, v101
	v_cvt_pk_bf16_f32 v100, v102, v103
	v_cvt_pk_bf16_f32 v101, v104, v105
	v_cvt_pk_bf16_f32 v102, v106, v107
	v_cvt_pk_bf16_f32 v103, v108, v109
	v_cvt_pk_bf16_f32 v104, v110, v111
	v_cvt_pk_bf16_f32 v105, v112, v113
	s_nop 0
	v_mfma_f32_32x32x16_bf16 v[34:49], v[146:149], v[98:101], v[34:49]
	v_mfma_f32_32x32x16_bf16 v[2:17], v[154:157], v[98:101], v[2:17]
	v_exp_f32_e32 v82, v82
	v_exp_f32_e32 v83, v83
	v_exp_f32_e32 v84, v84
	v_exp_f32_e32 v85, v85
	v_exp_f32_e32 v86, v86
	v_mfma_f32_32x32x16_bf16 v[34:49], v[150:153], v[102:105], v[34:49]
	v_exp_f32_e32 v87, v87
	v_exp_f32_e32 v88, v88
	v_exp_f32_e32 v89, v89
	v_exp_f32_e32 v90, v90
	v_exp_f32_e32 v91, v91
	v_mfma_f32_32x32x16_bf16 v[2:17], v[158:161], v[102:105], v[2:17]
	ds_read_b128 v[146:149], v195 offset:192
	ds_read_b128 v[150:153], v195 offset:224
	ds_read_b128 v[154:157], v194 offset:192
	ds_read_b128 v[158:161], v194 offset:224
	v_exp_f32_e32 v92, v92
	v_exp_f32_e32 v93, v93
	v_exp_f32_e32 v94, v94
	v_exp_f32_e32 v95, v95
	v_exp_f32_e32 v96, v96
	v_mfma_f32_32x32x16_bf16 v[98:113], v[238:241], v[130:133], v[18:33]
	v_exp_f32_e32 v97, v97
	v_add_f32_e32 v183, v82, v183
	v_add_f32_e32 v183, v83, v183
	v_add_f32_e32 v183, v84, v183
	v_add_f32_e32 v183, v85, v183
	v_mfma_f32_32x32x16_bf16 v[98:113], v[242:245], v[134:137], v[98:113]
	v_add_f32_e32 v183, v86, v183
	v_add_f32_e32 v183, v87, v183
	v_add_f32_e32 v183, v88, v183
	v_add_f32_e32 v183, v89, v183
	v_add_f32_e32 v183, v90, v183
	v_mfma_f32_32x32x16_bf16 v[98:113], v[246:249], v[138:141], v[98:113]
	v_add_f32_e32 v183, v91, v183
	v_add_f32_e32 v183, v92, v183
	v_add_f32_e32 v183, v93, v183
	v_add_f32_e32 v183, v94, v183
	v_add_f32_e32 v183, v95, v183
	v_mfma_f32_32x32x16_bf16 v[98:113], v[204:207], v[142:145], v[98:113]
	v_add_f32_e32 v183, v96, v183
	v_add_f32_e32 v183, v97, v183
	v_cvt_pk_bf16_f32 v82, v82, v83
	v_cvt_pk_bf16_f32 v83, v84, v85
	v_cvt_pk_bf16_f32 v84, v86, v87
	v_cvt_pk_bf16_f32 v85, v88, v89
	v_cvt_pk_bf16_f32 v86, v90, v91
	v_cvt_pk_bf16_f32 v87, v92, v93
	v_cvt_pk_bf16_f32 v88, v94, v95
	v_cvt_pk_bf16_f32 v89, v96, v97
	s_nop 0
	s_waitcnt lgkmcnt(0)
	v_mfma_f32_32x32x16_bf16 v[66:81], v[146:149], v[82:85], v[66:81]
	v_mfma_f32_32x32x16_bf16 v[50:65], v[154:157], v[82:85], v[50:65]
	v_exp_f32_e32 v98, v98
	v_exp_f32_e32 v99, v99
	v_exp_f32_e32 v100, v100
	v_exp_f32_e32 v101, v101
	v_exp_f32_e32 v102, v102
	v_mfma_f32_32x32x16_bf16 v[66:81], v[150:153], v[86:89], v[66:81]
	v_exp_f32_e32 v103, v103
	v_exp_f32_e32 v104, v104
	v_exp_f32_e32 v105, v105
	v_exp_f32_e32 v106, v106
	v_exp_f32_e32 v107, v107
	v_mfma_f32_32x32x16_bf16 v[50:65], v[158:161], v[86:89], v[50:65]
	v_exp_f32_e32 v108, v108
	v_exp_f32_e32 v109, v109
	v_exp_f32_e32 v110, v110
	v_exp_f32_e32 v111, v111
	v_exp_f32_e32 v112, v112
	v_exp_f32_e32 v113, v113
	v_add_f32_e32 v182, v98, v182
	v_add_f32_e32 v182, v99, v182
	v_add_f32_e32 v182, v100, v182
	v_add_f32_e32 v182, v101, v182
	v_add_f32_e32 v182, v102, v182
	v_add_f32_e32 v182, v103, v182
	v_add_f32_e32 v182, v104, v182
	v_add_f32_e32 v182, v105, v182
	v_add_f32_e32 v182, v106, v182
	v_add_f32_e32 v182, v107, v182
	v_add_f32_e32 v182, v108, v182
	v_add_f32_e32 v182, v109, v182
	v_add_f32_e32 v182, v110, v182
	v_add_f32_e32 v182, v111, v182
	v_add_f32_e32 v182, v112, v182
	v_add_f32_e32 v182, v113, v182
	v_cvt_pk_bf16_f32 v98, v98, v99
	v_cvt_pk_bf16_f32 v99, v100, v101
	v_cvt_pk_bf16_f32 v100, v102, v103
	v_cvt_pk_bf16_f32 v101, v104, v105
	v_cvt_pk_bf16_f32 v102, v106, v107
	v_cvt_pk_bf16_f32 v103, v108, v109
	v_cvt_pk_bf16_f32 v104, v110, v111
	v_cvt_pk_bf16_f32 v105, v112, v113
	s_nop 1
	v_mfma_f32_32x32x16_bf16 v[34:49], v[146:149], v[98:101], v[34:49]
	v_mfma_f32_32x32x16_bf16 v[2:17], v[154:157], v[98:101], v[2:17]
	v_mfma_f32_32x32x16_bf16 v[34:49], v[150:153], v[102:105], v[34:49]
	v_mfma_f32_32x32x16_bf16 v[2:17], v[158:161], v[102:105], v[2:17]
	s_movk_i32 s43, 0x100
	s_add_i32 s42, s42, s94
	s_cmpk_gt_i32 s42, 0x1ff
	s_cselect_b64 s[70:71], -1, 0
	s_cmpk_lt_i32 s42, 0x200
	s_cselect_b32 s43, s42, -1
	s_and_b32 s44, s43, 31
	s_cmp_gt_i32 s43, -1
	s_cselect_b64 s[46:47], -1, 0
	v_add_co_u32_e64 v0, s[48:49], s44, -1
	s_and_b64 s[68:69], s[46:47], s[48:49]
	s_waitcnt vmcnt(0) lgkmcnt(0)
	s_barrier
	s_cmp_lt_i32 s43, 0
	s_cbranch_scc1 .Lqpf_skip
	s_and_b32 s98, s43, 31
	s_lshl_b32 s98, s98, 7
	s_add_i32 s98, s98, s33
	s_ashr_i32 s99, s43, 7
	s_lshl_b32 s99, s99, 12
	s_add_i32 s98, s98, s99
	s_lshl_b32 s98, s98, 11
	s_bfe_u32 s99, s43, 0x20005
	s_lshl_b32 s99, s99, 2
	v_readlane_b32 vcc_lo, v251, 40
	s_nop 3
	s_or_b32 s99, s99, vcc_lo
	s_lshl_b32 s99, s99, 7
	s_add_u32 s98, s98, s99
	v_lshl_add_u32 v252, v170, 11, s98
	v_readlane_b32 s98, v251, 63
	v_readlane_b32 s99, v250, 0
	s_nop 7
	global_load_dword v252, v252, s[98:99]

; #define LAS __attribute__((address_space(3)))
; __device__ __forceinline__ bool attn_unit(const Ptrs& P, LAS unsigned char* lds, int unit, int tid, int wave, int lane, bool pre, int nxt) {
;     ...
;         const LAS unsigned char* Kl = lds + (c % 3) * AT_BUF; const LAS unsigned char* Vl = Kl + AT_KB;
; #pragma unroll 1
;         for (int kt = 0; kt < 4; ++kt) {
;             if (c == 0 && 32 * kt + 31 < q0) continue;
;             if (c == 2 && 32 * kt > q0 + 63) continue;
;             bf16x8_t kf[4], vf[2][2];
; #pragma unroll
;             for (int ds = 0; ds < 4; ++ds) kf[ds] = *(const LAS bf16x8_t*)(Kl + (32 * kt + r) * AT_KP + (16 * ds + 8 * hh) * 2);
; #pragma unroll
;             for (int db = 0; db < 2; ++db)
; #pragma unroll
;                 for (int s = 0; s < 2; ++s) vf[db][s] = *(const LAS bf16x8_t*)(Vl + (32 * db + r) * AT_VP + (32 * kt + 16 * s + 8 * hh) * 2);
; #pragma unroll
;             for (int cb = 0; cb < 2; ++cb) {
;                 const int dq = 32 * kt - (q0 + 32 * cb);
;                 if ((c == 0 && dq < 0) || (c == 2 && dq > 0)) continue;
;                 const bool diag = (c == 0 || c == 2) && dq == 0;
;                 f32x16 st = MFMA32(kf[0], qf[cb][0], negm);
;                 st = MFMA32(kf[1], qf[cb][1], st); st = MFMA32(kf[2], qf[cb][2], st); st = MFMA32(kf[3], qf[cb][3], st);
;                 float p[16];
; #pragma unroll
;                 for (int i = 0; i < 16; ++i) p[i] = __builtin_amdgcn_exp2f(st[i]);
;                 if (diag) {
;                     const int thr = r - 4 * hh;
; #pragma unroll
;                     for (int i = 0; i < 16; ++i) { const bool vis = c == 0 ? crow(i, 0) >= thr : crow(i, 0) <= thr; p[i] = vis ? p[i] : 0.f; }
;                 }
;                 float s4 = 0.f;
; #pragma unroll
;                 for (int i = 0; i < 16; ++i) s4 += p[i];
;                 rs[cb] += s4;
; #pragma unroll
;                 for (int s = 0; s < 2; ++s) {
;                     u32x4 w; w.x = cvtpk(p[8 * s], p[8 * s + 1]); w.y = cvtpk(p[8 * s + 2], p[8 * s + 3]); w.z = cvtpk(p[8 * s + 4], p[8 * s + 5]); w.w = cvtpk(p[8 * s + 6], p[8 * s + 7]);
;                     const bf16x8_t pb = __builtin_bit_cast(bf16x8_t, w);
;                     o[0][cb] = MFMA32(vf[0][s], pb, o[0][cb]); o[1][cb] = MFMA32(vf[1][s], pb, o[1][cb]);
;                 }
;             }
;         }
.LBB9_411:
	ds_read_b128 v[238:241], v199 offset:0
	ds_read_b128 v[242:245], v199 offset:32
	ds_read_b128 v[246:249], v199 offset:64
	ds_read_b128 v[204:207], v199 offset:96
	s_waitcnt lgkmcnt(0)
	v_mfma_f32_32x32x16_bf16 v[82:97], v[238:241], v[114:117], v[18:33]
	v_mfma_f32_32x32x16_bf16 v[82:97], v[242:245], v[118:121], v[82:97]
	v_mfma_f32_32x32x16_bf16 v[82:97], v[246:249], v[122:125], v[82:97]
	v_mfma_f32_32x32x16_bf16 v[82:97], v[204:207], v[126:129], v[82:97]
	v_mfma_f32_32x32x16_bf16 v[98:113], v[238:241], v[130:133], v[18:33]
	v_mfma_f32_32x32x16_bf16 v[98:113], v[242:245], v[134:137], v[98:113]
	v_mfma_f32_32x32x16_bf16 v[98:113], v[246:249], v[138:141], v[98:113]
	v_mfma_f32_32x32x16_bf16 v[98:113], v[204:207], v[142:145], v[98:113]
	ds_read_b128 v[146:149], v198 offset:0
	ds_read_b128 v[150:153], v198 offset:32
	ds_read_b128 v[154:157], v197 offset:0
	ds_read_b128 v[158:161], v197 offset:32
	ds_read_b128 v[238:241], v199 offset:4608
	ds_read_b128 v[242:245], v199 offset:4640
	ds_read_b128 v[246:249], v199 offset:4672
	ds_read_b128 v[204:207], v199 offset:4704
	v_exp_f32_e32 v82, v82
	v_exp_f32_e32 v83, v83
	v_exp_f32_e32 v84, v84
	v_exp_f32_e32 v85, v85
	v_exp_f32_e32 v86, v86
	v_exp_f32_e32 v87, v87
	v_exp_f32_e32 v88, v88
	v_exp_f32_e32 v89, v89
	v_exp_f32_e32 v90, v90
	v_exp_f32_e32 v91, v91
	v_exp_f32_e32 v92, v92
	v_exp_f32_e32 v93, v93
	v_exp_f32_e32 v94, v94
	v_exp_f32_e32 v95, v95
	v_exp_f32_e32 v96, v96
	v_exp_f32_e32 v97, v97
	v_add_f32_e32 v183, v82, v183
	v_add_f32_e32 v183, v83, v183
	v_add_f32_e32 v183, v84, v183
	v_add_f32_e32 v183, v85, v183
	v_add_f32_e32 v183, v86, v183
	v_add_f32_e32 v183, v87, v183
	v_add_f32_e32 v183, v88, v183
	v_add_f32_e32 v183, v89, v183
	v_add_f32_e32 v183, v90, v183
	v_add_f32_e32 v183, v91, v183
	v_add_f32_e32 v183, v92, v183
	v_add_f32_e32 v183, v93, v183
	v_add_f32_e32 v183, v94, v183
	v_add_f32_e32 v183, v95, v183
	v_add_f32_e32 v183, v96, v183
	v_add_f32_e32 v183, v97, v183
	v_cvt_pk_bf16_f32 v82, v82, v83
	v_cvt_pk_bf16_f32 v83, v84, v85
	v_cvt_pk_bf16_f32 v84, v86, v87
	v_cvt_pk_bf16_f32 v85, v88, v89
	v_cvt_pk_bf16_f32 v86, v90, v91
	v_cvt_pk_bf16_f32 v87, v92, v93
	v_cvt_pk_bf16_f32 v88, v94, v95
	v_cvt_pk_bf16_f32 v89, v96, v97
	s_nop 0
	s_waitcnt lgkmcnt(4)
	v_mfma_f32_32x32x16_bf16 v[66:81], v[146:149], v[82:85], v[66:81]
	v_mfma_f32_32x32x16_bf16 v[50:65], v[154:157], v[82:85], v[50:65]
	v_exp_f32_e32 v98, v98
	v_exp_f32_e32 v99, v99
	v_exp_f32_e32 v100, v100
	v_exp_f32_e32 v101, v101
	v_exp_f32_e32 v102, v102
	v_mfma_f32_32x32x16_bf16 v[66:81], v[150:153], v[86:89], v[66:81]
	v_exp_f32_e32 v103, v103
	v_exp_f32_e32 v104, v104
	v_exp_f32_e32 v105, v105
	v_exp_f32_e32 v106, v106
	v_exp_f32_e32 v107, v107
	v_mfma_f32_32x32x16_bf16 v[50:65], v[158:161], v[86:89], v[50:65]
	v_exp_f32_e32 v108, v108
	v_exp_f32_e32 v109, v109
	v_exp_f32_e32 v110, v110
	v_exp_f32_e32 v111, v111
	v_exp_f32_e32 v112, v112
	s_waitcnt lgkmcnt(0)
	v_mfma_f32_32x32x16_bf16 v[82:97], v[238:241], v[114:117], v[18:33]
	v_exp_f32_e32 v113, v113
	v_add_f32_e32 v182, v98, v182
	v_add_f32_e32 v182, v99, v182
	v_add_f32_e32 v182, v100, v182
	v_add_f32_e32 v182, v101, v182
	v_mfma_f32_32x32x16_bf16 v[82:97], v[242:245], v[118:121], v[82:97]
	v_add_f32_e32 v182, v102, v182
	v_add_f32_e32 v182, v103, v182
	v_add_f32_e32 v182, v104, v182
	v_add_f32_e32 v182, v105, v182
	v_add_f32_e32 v182, v106, v182
	v_mfma_f32_32x32x16_bf16 v[82:97], v[246:249], v[122:125], v[82:97]
	v_add_f32_e32 v182, v107, v182
	v_add_f32_e32 v182, v108, v182
	v_add_f32_e32 v182, v109, v182
	v_add_f32_e32 v182, v110, v182
	v_add_f32_e32 v182, v111, v182
	v_mfma_f32_32x32x16_bf16 v[82:97], v[204:207], v[126:129], v[82:97]
	v_add_f32_e32 v182, v112, v182
	v_add_f32_e32 v182, v113, v182
	v_cvt_pk_bf16_f32 v98, v98, v99
	v_cvt_pk_bf16_f32 v99, v100, v101
	v_cvt_pk_bf16_f32 v100, v102, v103
	v_cvt_pk_bf16_f32 v101, v104, v105
	v_cvt_pk_bf16_f32 v102, v106, v107
	v_cvt_pk_bf16_f32 v103, v108, v109
	v_cvt_pk_bf16_f32 v104, v110, v111
	v_cvt_pk_bf16_f32 v105, v112, v113
	s_nop 0
	v_mfma_f32_32x32x16_bf16 v[34:49], v[146:149], v[98:101], v[34:49]
	v_mfma_f32_32x32x16_bf16 v[2:17], v[154:157], v[98:101], v[2:17]
	v_exp_f32_e32 v82, v82
	v_exp_f32_e32 v83, v83
	v_exp_f32_e32 v84, v84
	v_exp_f32_e32 v85, v85
	v_exp_f32_e32 v86, v86
	v_mfma_f32_32x32x16_bf16 v[34:49], v[150:153], v[102:105], v[34:49]
	v_exp_f32_e32 v87, v87
	v_exp_f32_e32 v88, v88
	v_exp_f32_e32 v89, v89
	v_exp_f32_e32 v90, v90
	v_exp_f32_e32 v91, v91
	v_mfma_f32_32x32x16_bf16 v[2:17], v[158:161], v[102:105], v[2:17]
	ds_read_b128 v[146:149], v198 offset:64
	ds_read_b128 v[150:153], v198 offset:96
	ds_read_b128 v[154:157], v197 offset:64
	ds_read_b128 v[158:161], v197 offset:96
	v_exp_f32_e32 v92, v92
	v_exp_f32_e32 v93, v93
	v_exp_f32_e32 v94, v94
	v_exp_f32_e32 v95, v95
	v_exp_f32_e32 v96, v96
	v_mfma_f32_32x32x16_bf16 v[98:113], v[238:241], v[130:133], v[18:33]
	v_exp_f32_e32 v97, v97
	v_add_f32_e32 v183, v82, v183
	v_add_f32_e32 v183, v83, v183
	v_add_f32_e32 v183, v84, v183
	v_add_f32_e32 v183, v85, v183
	v_mfma_f32_32x32x16_bf16 v[98:113], v[242:245], v[134:137], v[98:113]
	v_add_f32_e32 v183, v86, v183
	v_add_f32_e32 v183, v87, v183
	v_add_f32_e32 v183, v88, v183
	v_add_f32_e32 v183, v89, v183
	v_add_f32_e32 v183, v90, v183
	v_mfma_f32_32x32x16_bf16 v[98:113], v[246:249], v[138:141], v[98:113]
	v_add_f32_e32 v183, v91, v183
	v_add_f32_e32 v183, v92, v183
	v_add_f32_e32 v183, v93, v183
	v_add_f32_e32 v183, v94, v183
	v_add_f32_e32 v183, v95, v183
	v_mfma_f32_32x32x16_bf16 v[98:113], v[204:207], v[142:145], v[98:113]
	ds_read_b128 v[238:241], v199 offset:9216
	ds_read_b128 v[242:245], v199 offset:9248
	ds_read_b128 v[246:249], v199 offset:9280
	ds_read_b128 v[204:207], v199 offset:9312
	v_add_f32_e32 v183, v96, v183
	v_add_f32_e32 v183, v97, v183
	v_cvt_pk_bf16_f32 v82, v82, v83
	v_cvt_pk_bf16_f32 v83, v84, v85
	v_cvt_pk_bf16_f32 v84, v86, v87
	v_cvt_pk_bf16_f32 v85, v88, v89
	v_cvt_pk_bf16_f32 v86, v90, v91
	v_cvt_pk_bf16_f32 v87, v92, v93
	v_cvt_pk_bf16_f32 v88, v94, v95
	v_cvt_pk_bf16_f32 v89, v96, v97
	s_nop 0
	s_waitcnt lgkmcnt(4)
; __device__ __forceinline__ unsigned cvtpk(float lo, float hi) { f32x2_t v = {lo, hi}; bf16x2_t b = __builtin_convertvector(v, bf16x2_t); return __builtin_bit_cast(unsigned, b); }
; __device__ __forceinline__ bool attn_unit(const Ptrs& P, LAS unsigned char* lds, int unit, int tid, int wave, int lane, bool pre, int nxt) {
;     ...
;         for (int kt = 0; kt < 4; ++kt) {
;             if (c == 0 && 32 * kt + 31 < q0) continue;
;             if (c == 2 && 32 * kt > q0 + 63) continue;
;             bf16x8_t kf[4], vf[2][2];
; #pragma unroll
;             for (int ds = 0; ds < 4; ++ds) kf[ds] = *(const LAS bf16x8_t*)(Kl + (32 * kt + r) * AT_KP + (16 * ds + 8 * hh) * 2);
; #pragma unroll
;             for (int db = 0; db < 2; ++db)
; #pragma unroll
;                 for (int s = 0; s < 2; ++s) vf[db][s] = *(const LAS bf16x8_t*)(Vl + (32 * db + r) * AT_VP + (32 * kt + 16 * s + 8 * hh) * 2);
; #pragma unroll
;             for (int cb = 0; cb < 2; ++cb) {
;                 const int dq = 32 * kt - (q0 + 32 * cb);
;                 if ((c == 0 && dq < 0) || (c == 2 && dq > 0)) continue;
;                 const bool diag = (c == 0 || c == 2) && dq == 0;
;                 f32x16 st = MFMA32(kf[0], qf[cb][0], negm);
;                 st = MFMA32(kf[1], qf[cb][1], st); st = MFMA32(kf[2], qf[cb][2], st); st = MFMA32(kf[3], qf[cb][3], st);
;                 float p[16];
; #pragma unroll
;                 for (int i = 0; i < 16; ++i) p[i] = __builtin_amdgcn_exp2f(st[i]);
;                 if (diag) {
;                     const int thr = r - 4 * hh;
; #pragma unroll
;                     for (int i = 0; i < 16; ++i) { const bool vis = c == 0 ? crow(i, 0) >= thr : crow(i, 0) <= thr; p[i] = vis ? p[i] : 0.f; }
;                 }
;                 float s4 = 0.f;
; #pragma unroll
;                 for (int i = 0; i < 16; ++i) s4 += p[i];
;                 rs[cb] += s4;
; #pragma unroll
;                 for (int s = 0; s < 2; ++s) {
;                     u32x4 w; w.x = cvtpk(p[8 * s], p[8 * s + 1]); w.y = cvtpk(p[8 * s + 2], p[8 * s + 3]); w.z = cvtpk(p[8 * s + 4], p[8 * s + 5]); w.w = cvtpk(p[8 * s + 6], p[8 * s + 7]);
;                     const bf16x8_t pb = __builtin_bit_cast(bf16x8_t, w);
;                     o[0][cb] = MFMA32(vf[0][s], pb, o[0][cb]); o[1][cb] = MFMA32(vf[1][s], pb, o[1][cb]);
;                 }
;             }
;         }
	v_mfma_f32_32x32x16_bf16 v[66:81], v[146:149], v[82:85], v[66:81]
	v_mfma_f32_32x32x16_bf16 v[50:65], v[154:157], v[82:85], v[50:65]
	v_exp_f32_e32 v98, v98
	v_exp_f32_e32 v99, v99
	v_exp_f32_e32 v100, v100
	v_exp_f32_e32 v101, v101
	v_exp_f32_e32 v102, v102
	v_mfma_f32_32x32x16_bf16 v[66:81], v[150:153], v[86:89], v[66:81]
	v_exp_f32_e32 v103, v103
	v_exp_f32_e32 v104, v104
	v_exp_f32_e32 v105, v105
	v_exp_f32_e32 v106, v106
	v_exp_f32_e32 v107, v107
	v_mfma_f32_32x32x16_bf16 v[50:65], v[158:161], v[86:89], v[50:65]
	v_exp_f32_e32 v108, v108
	v_exp_f32_e32 v109, v109
	v_exp_f32_e32 v110, v110
	v_exp_f32_e32 v111, v111
	v_exp_f32_e32 v112, v112
	s_waitcnt lgkmcnt(0)
	v_mfma_f32_32x32x16_bf16 v[82:97], v[238:241], v[114:117], v[18:33]
	v_exp_f32_e32 v113, v113
	v_add_f32_e32 v182, v98, v182
	v_add_f32_e32 v182, v99, v182
	v_add_f32_e32 v182, v100, v182
	v_add_f32_e32 v182, v101, v182
	v_mfma_f32_32x32x16_bf16 v[82:97], v[242:245], v[118:121], v[82:97]
	v_add_f32_e32 v182, v102, v182
	v_add_f32_e32 v182, v103, v182
	v_add_f32_e32 v182, v104, v182
	v_add_f32_e32 v182, v105, v182
	v_add_f32_e32 v182, v106, v182
	v_mfma_f32_32x32x16_bf16 v[82:97], v[246:249], v[122:125], v[82:97]
	v_add_f32_e32 v182, v107, v182
	v_add_f32_e32 v182, v108, v182
	v_add_f32_e32 v182, v109, v182
	v_add_f32_e32 v182, v110, v182
	v_add_f32_e32 v182, v111, v182
	v_mfma_f32_32x32x16_bf16 v[82:97], v[204:207], v[126:129], v[82:97]
	v_add_f32_e32 v182, v112, v182
	v_add_f32_e32 v182, v113, v182
	v_cvt_pk_bf16_f32 v98, v98, v99
	v_cvt_pk_bf16_f32 v99, v100, v101
	v_cvt_pk_bf16_f32 v100, v102, v103
	v_cvt_pk_bf16_f32 v101, v104, v105
	v_cvt_pk_bf16_f32 v102, v106, v107
	v_cvt_pk_bf16_f32 v103, v108, v109
	v_cvt_pk_bf16_f32 v104, v110, v111
	v_cvt_pk_bf16_f32 v105, v112, v113
	s_nop 0
	v_mfma_f32_32x32x16_bf16 v[34:49], v[146:149], v[98:101], v[34:49]
	v_mfma_f32_32x32x16_bf16 v[2:17], v[154:157], v[98:101], v[2:17]
	v_exp_f32_e32 v82, v82
	v_exp_f32_e32 v83, v83
	v_exp_f32_e32 v84, v84
	v_exp_f32_e32 v85, v85
	v_exp_f32_e32 v86, v86
	v_mfma_f32_32x32x16_bf16 v[34:49], v[150:153], v[102:105], v[34:49]
	v_exp_f32_e32 v87, v87
	v_exp_f32_e32 v88, v88
	v_exp_f32_e32 v89, v89
	v_exp_f32_e32 v90, v90
	v_exp_f32_e32 v91, v91
	v_mfma_f32_32x32x16_bf16 v[2:17], v[158:161], v[102:105], v[2:17]
	ds_read_b128 v[146:149], v198 offset:128
	ds_read_b128 v[150:153], v198 offset:160
	ds_read_b128 v[154:157], v197 offset:128
	ds_read_b128 v[158:161], v197 offset:160
	v_exp_f32_e32 v92, v92
	v_exp_f32_e32 v93, v93
	v_exp_f32_e32 v94, v94
	v_exp_f32_e32 v95, v95
	v_exp_f32_e32 v96, v96
	v_mfma_f32_32x32x16_bf16 v[98:113], v[238:241], v[130:133], v[18:33]
	v_exp_f32_e32 v97, v97
	v_add_f32_e32 v183, v82, v183
	v_add_f32_e32 v183, v83, v183
	v_add_f32_e32 v183, v84, v183
	v_add_f32_e32 v183, v85, v183
	v_mfma_f32_32x32x16_bf16 v[98:113], v[242:245], v[134:137], v[98:113]
	v_add_f32_e32 v183, v86, v183
	v_add_f32_e32 v183, v87, v183
	v_add_f32_e32 v183, v88, v183
	v_add_f32_e32 v183, v89, v183
	v_add_f32_e32 v183, v90, v183
	v_mfma_f32_32x32x16_bf16 v[98:113], v[246:249], v[138:141], v[98:113]
	v_add_f32_e32 v183, v91, v183
	v_add_f32_e32 v183, v92, v183
	v_add_f32_e32 v183, v93, v183
	v_add_f32_e32 v183, v94, v183
	v_add_f32_e32 v183, v95, v183
	v_mfma_f32_32x32x16_bf16 v[98:113], v[204:207], v[142:145], v[98:113]
	ds_read_b128 v[238:241], v199 offset:13824
	ds_read_b128 v[242:245], v199 offset:13856
	ds_read_b128 v[246:249], v199 offset:13888
	ds_read_b128 v[204:207], v199 offset:13920
	v_add_f32_e32 v183, v96, v183
	v_add_f32_e32 v183, v97, v183
	v_cvt_pk_bf16_f32 v82, v82, v83
	v_cvt_pk_bf16_f32 v83, v84, v85
	v_cvt_pk_bf16_f32 v84, v86, v87
	v_cvt_pk_bf16_f32 v85, v88, v89
	v_cvt_pk_bf16_f32 v86, v90, v91
	v_cvt_pk_bf16_f32 v87, v92, v93
	v_cvt_pk_bf16_f32 v88, v94, v95
	v_cvt_pk_bf16_f32 v89, v96, v97
	s_nop 0
	s_waitcnt lgkmcnt(4)
	v_mfma_f32_32x32x16_bf16 v[66:81], v[146:149], v[82:85], v[66:81]
	v_mfma_f32_32x32x16_bf16 v[50:65], v[154:157], v[82:85], v[50:65]
	v_exp_f32_e32 v98, v98
	v_exp_f32_e32 v99, v99
	v_exp_f32_e32 v100, v100
	v_exp_f32_e32 v101, v101
	v_exp_f32_e32 v102, v102
	v_mfma_f32_32x32x16_bf16 v[66:81], v[150:153], v[86:89], v[66:81]
	v_exp_f32_e32 v103, v103
	v_exp_f32_e32 v104, v104
	v_exp_f32_e32 v105, v105
	v_exp_f32_e32 v106, v106
	v_exp_f32_e32 v107, v107
	v_mfma_f32_32x32x16_bf16 v[50:65], v[158:161], v[86:89], v[50:65]
	v_exp_f32_e32 v108, v108
	v_exp_f32_e32 v109, v109
	v_exp_f32_e32 v110, v110
	v_exp_f32_e32 v111, v111
	v_exp_f32_e32 v112, v112
	s_waitcnt lgkmcnt(0)
; #define LAS __attribute__((address_space(3)))
; __device__ __forceinline__ bool attn_unit(const Ptrs& P, LAS unsigned char* lds, int unit, int tid, int wave, int lane, bool pre, int nxt) {
;     ...
;         for (int kt = 0; kt < 4; ++kt) {
;             if (c == 0 && 32 * kt + 31 < q0) continue;
;             if (c == 2 && 32 * kt > q0 + 63) continue;
;             bf16x8_t kf[4], vf[2][2];
; #pragma unroll
;             for (int ds = 0; ds < 4; ++ds) kf[ds] = *(const LAS bf16x8_t*)(Kl + (32 * kt + r) * AT_KP + (16 * ds + 8 * hh) * 2);
; #pragma unroll
;             for (int db = 0; db < 2; ++db)
; #pragma unroll
;                 for (int s = 0; s < 2; ++s) vf[db][s] = *(const LAS bf16x8_t*)(Vl + (32 * db + r) * AT_VP + (32 * kt + 16 * s + 8 * hh) * 2);
; #pragma unroll
;             for (int cb = 0; cb < 2; ++cb) {
;                 const int dq = 32 * kt - (q0 + 32 * cb);
;                 if ((c == 0 && dq < 0) || (c == 2 && dq > 0)) continue;
;                 const bool diag = (c == 0 || c == 2) && dq == 0;
;                 f32x16 st = MFMA32(kf[0], qf[cb][0], negm);
;                 st = MFMA32(kf[1], qf[cb][1], st); st = MFMA32(kf[2], qf[cb][2], st); st = MFMA32(kf[3], qf[cb][3], st);
;                 float p[16];
; #pragma unroll
;                 for (int i = 0; i < 16; ++i) p[i] = __builtin_amdgcn_exp2f(st[i]);
;                 if (diag) {
;                     const int thr = r - 4 * hh;
; #pragma unroll
;                     for (int i = 0; i < 16; ++i) { const bool vis = c == 0 ? crow(i, 0) >= thr : crow(i, 0) <= thr; p[i] = vis ? p[i] : 0.f; }
;                 }
;                 float s4 = 0.f;
; #pragma unroll
;                 for (int i = 0; i < 16; ++i) s4 += p[i];
;                 rs[cb] += s4;
; #pragma unroll
;                 for (int s = 0; s < 2; ++s) {
;                     u32x4 w; w.x = cvtpk(p[8 * s], p[8 * s + 1]); w.y = cvtpk(p[8 * s + 2], p[8 * s + 3]); w.z = cvtpk(p[8 * s + 4], p[8 * s + 5]); w.w = cvtpk(p[8 * s + 6], p[8 * s + 7]);
;                     const bf16x8_t pb = __builtin_bit_cast(bf16x8_t, w);
;                     o[0][cb] = MFMA32(vf[0][s], pb, o[0][cb]); o[1][cb] = MFMA32(vf[1][s], pb, o[1][cb]);
;                 }
;             }
;         }
;         AT_SYNC();
;     ...
;     const float sk = __builtin_amdgcn_exp2f(sink2 - mshift);
; #pragma unroll
;     for (int cb = 0; cb < 2; ++cb) {
	v_mfma_f32_32x32x16_bf16 v[82:97], v[238:241], v[114:117], v[18:33]
	v_exp_f32_e32 v113, v113
	v_add_f32_e32 v182, v98, v182
	v_add_f32_e32 v182, v99, v182
	v_add_f32_e32 v182, v100, v182
	v_add_f32_e32 v182, v101, v182
	v_mfma_f32_32x32x16_bf16 v[82:97], v[242:245], v[118:121], v[82:97]
	v_add_f32_e32 v182, v102, v182
	v_add_f32_e32 v182, v103, v182
	v_add_f32_e32 v182, v104, v182
	v_add_f32_e32 v182, v105, v182
	v_add_f32_e32 v182, v106, v182
	v_mfma_f32_32x32x16_bf16 v[82:97], v[246:249], v[122:125], v[82:97]
	v_add_f32_e32 v182, v107, v182
	v_add_f32_e32 v182, v108, v182
	v_add_f32_e32 v182, v109, v182
	v_add_f32_e32 v182, v110, v182
	v_add_f32_e32 v182, v111, v182
	v_mfma_f32_32x32x16_bf16 v[82:97], v[204:207], v[126:129], v[82:97]
	v_add_f32_e32 v182, v112, v182
	v_add_f32_e32 v182, v113, v182
	v_cvt_pk_bf16_f32 v98, v98, v99
	v_cvt_pk_bf16_f32 v99, v100, v101
	v_cvt_pk_bf16_f32 v100, v102, v103
	v_cvt_pk_bf16_f32 v101, v104, v105
	v_cvt_pk_bf16_f32 v102, v106, v107
	v_cvt_pk_bf16_f32 v103, v108, v109
	v_cvt_pk_bf16_f32 v104, v110, v111
	v_cvt_pk_bf16_f32 v105, v112, v113
	s_nop 0
	v_mfma_f32_32x32x16_bf16 v[34:49], v[146:149], v[98:101], v[34:49]
	v_mfma_f32_32x32x16_bf16 v[2:17], v[154:157], v[98:101], v[2:17]
	v_exp_f32_e32 v82, v82
	v_exp_f32_e32 v83, v83
	v_exp_f32_e32 v84, v84
	v_exp_f32_e32 v85, v85
	v_exp_f32_e32 v86, v86
	v_mfma_f32_32x32x16_bf16 v[34:49], v[150:153], v[102:105], v[34:49]
	v_exp_f32_e32 v87, v87
	v_exp_f32_e32 v88, v88
	v_exp_f32_e32 v89, v89
	v_exp_f32_e32 v90, v90
	v_exp_f32_e32 v91, v91
	v_mfma_f32_32x32x16_bf16 v[2:17], v[158:161], v[102:105], v[2:17]
	ds_read_b128 v[146:149], v198 offset:192
	ds_read_b128 v[150:153], v198 offset:224
	ds_read_b128 v[154:157], v197 offset:192
	ds_read_b128 v[158:161], v197 offset:224
	v_exp_f32_e32 v92, v92
	v_exp_f32_e32 v93, v93
	v_exp_f32_e32 v94, v94
	v_exp_f32_e32 v95, v95
	v_exp_f32_e32 v96, v96
	v_mfma_f32_32x32x16_bf16 v[98:113], v[238:241], v[130:133], v[18:33]
	v_exp_f32_e32 v97, v97
	v_add_f32_e32 v183, v82, v183
	v_add_f32_e32 v183, v83, v183
	v_add_f32_e32 v183, v84, v183
	v_add_f32_e32 v183, v85, v183
	v_mfma_f32_32x32x16_bf16 v[98:113], v[242:245], v[134:137], v[98:113]
	v_add_f32_e32 v183, v86, v183
	v_add_f32_e32 v183, v87, v183
	v_add_f32_e32 v183, v88, v183
	v_add_f32_e32 v183, v89, v183
	v_add_f32_e32 v183, v90, v183
	v_mfma_f32_32x32x16_bf16 v[98:113], v[246:249], v[138:141], v[98:113]
	v_add_f32_e32 v183, v91, v183
	v_add_f32_e32 v183, v92, v183
	v_add_f32_e32 v183, v93, v183
	v_add_f32_e32 v183, v94, v183
	v_add_f32_e32 v183, v95, v183
	v_mfma_f32_32x32x16_bf16 v[98:113], v[204:207], v[142:145], v[98:113]
	v_add_f32_e32 v183, v96, v183
	v_add_f32_e32 v183, v97, v183
	v_cvt_pk_bf16_f32 v82, v82, v83
	v_cvt_pk_bf16_f32 v83, v84, v85
	v_cvt_pk_bf16_f32 v84, v86, v87
	v_cvt_pk_bf16_f32 v85, v88, v89
	v_cvt_pk_bf16_f32 v86, v90, v91
	v_cvt_pk_bf16_f32 v87, v92, v93
	v_cvt_pk_bf16_f32 v88, v94, v95
	v_cvt_pk_bf16_f32 v89, v96, v97
	s_nop 0
	s_waitcnt lgkmcnt(0)
	v_mfma_f32_32x32x16_bf16 v[66:81], v[146:149], v[82:85], v[66:81]
	v_mfma_f32_32x32x16_bf16 v[50:65], v[154:157], v[82:85], v[50:65]
	v_exp_f32_e32 v98, v98
	v_exp_f32_e32 v99, v99
	v_exp_f32_e32 v100, v100
	v_exp_f32_e32 v101, v101
	v_exp_f32_e32 v102, v102
	v_mfma_f32_32x32x16_bf16 v[66:81], v[150:153], v[86:89], v[66:81]
	v_exp_f32_e32 v103, v103
	v_exp_f32_e32 v104, v104
	v_exp_f32_e32 v105, v105
	v_exp_f32_e32 v106, v106
	v_exp_f32_e32 v107, v107
	v_mfma_f32_32x32x16_bf16 v[50:65], v[158:161], v[86:89], v[50:65]
	v_exp_f32_e32 v108, v108
	v_exp_f32_e32 v109, v109
	v_exp_f32_e32 v110, v110
	v_exp_f32_e32 v111, v111
	v_exp_f32_e32 v112, v112
	v_exp_f32_e32 v113, v113
	v_add_f32_e32 v182, v98, v182
	v_add_f32_e32 v182, v99, v182
	v_add_f32_e32 v182, v100, v182
	v_add_f32_e32 v182, v101, v182
	v_add_f32_e32 v182, v102, v182
	v_add_f32_e32 v182, v103, v182
	v_add_f32_e32 v182, v104, v182
	v_add_f32_e32 v182, v105, v182
	v_add_f32_e32 v182, v106, v182
	v_add_f32_e32 v182, v107, v182
	v_add_f32_e32 v182, v108, v182
	v_add_f32_e32 v182, v109, v182
	v_add_f32_e32 v182, v110, v182
	v_add_f32_e32 v182, v111, v182
	v_add_f32_e32 v182, v112, v182
	v_add_f32_e32 v182, v113, v182
	v_cvt_pk_bf16_f32 v98, v98, v99
	v_cvt_pk_bf16_f32 v99, v100, v101
	v_cvt_pk_bf16_f32 v100, v102, v103
	v_cvt_pk_bf16_f32 v101, v104, v105
	v_cvt_pk_bf16_f32 v102, v106, v107
	v_cvt_pk_bf16_f32 v103, v108, v109
	v_cvt_pk_bf16_f32 v104, v110, v111
	v_cvt_pk_bf16_f32 v105, v112, v113
	s_nop 1
	v_mfma_f32_32x32x16_bf16 v[34:49], v[146:149], v[98:101], v[34:49]
	v_mfma_f32_32x32x16_bf16 v[2:17], v[154:157], v[98:101], v[2:17]
	v_mfma_f32_32x32x16_bf16 v[34:49], v[150:153], v[102:105], v[34:49]
	v_mfma_f32_32x32x16_bf16 v[2:17], v[158:161], v[102:105], v[2:17]
	s_movk_i32 s43, 0x100
	v_sub_f32_e32 v0, v177, v203
	v_exp_f32_e32 v28, v0
	ds_bpermute_b32 v0, v190, v183
	v_readlane_b32 s40, v250, 17
	s_lshl_b32 s43, s45, 1
	v_mov_b32_e32 v177, v1
	v_or_b32_e32 v22, s40, v171
	s_waitcnt lgkmcnt(0)
	v_add_f32_e32 v0, v183, v0
	v_add_f32_e32 v0, v28, v0
	v_rcp_f32_e32 v0, v0
	v_readlane_b32 s40, v250, 5
	s_add_u32 s80, s40, s43
	v_readlane_b32 s40, v250, 6
	v_ashrrev_i32_e32 v23, 31, v22
	s_addc_u32 s81, s40, 0
	v_lshlrev_b64 v[18:19], 11, v[22:23]
	v_lshl_add_u64 v[24:25], s[80:81], 0, v[18:19]
	v_pk_mul_f32 v[18:19], v[66:67], v[0:1] op_sel_hi:[1,0]
	v_pk_mul_f32 v[20:21], v[68:69], v[0:1] op_sel_hi:[1,0]
	v_cvt_pk_bf16_f32 v18, v18, v19
	v_cvt_pk_bf16_f32 v19, v20, v21
	v_pk_mul_f32 v[20:21], v[70:71], v[0:1] op_sel_hi:[1,0]
	v_pk_mul_f32 v[26:27], v[72:73], v[0:1] op_sel_hi:[1,0]
	v_cvt_pk_bf16_f32 v20, v20, v21
	v_cvt_pk_bf16_f32 v21, v26, v27
	s_nop 0
	v_permlane32_swap_b32_e32 v18, v20
	v_permlane32_swap_b32_e32 v19, v21
	v_lshl_add_u64 v[24:25], v[24:25], 0, v[176:177]
	s_waitcnt vmcnt(0) lgkmcnt(0)
	s_barrier
; __device__ __forceinline__ unsigned cvtpk(float lo, float hi) { f32x2_t v = {lo, hi}; bf16x2_t b = __builtin_convertvector(v, bf16x2_t); return __builtin_bit_cast(unsigned, b); }
; __device__ __forceinline__ bool attn_unit(const Ptrs& P, LAS unsigned char* lds, int unit, int tid, int wave, int lane, bool pre, int nxt) {
;     ...
;     const float sk = __builtin_amdgcn_exp2f(sink2 - mshift);
; #pragma unroll
;     for (int cb = 0; cb < 2; ++cb) {
;         const float den = rs[cb] + __shfl_xor(rs[cb], 32) + sk; const float inv = __builtin_amdgcn_rcpf(den);
;         bf16_t* orow = (bf16_t*)(ws + WS_ATT) + (size_t)(b * SEQ + n * 128 + q0 + 32 * cb + r) * DM + h * 64;
; #pragma unroll
;         for (int db = 0; db < 2; ++db)
; #pragma unroll
;             for (int p = 0; p < 2; ++p) { u32x2 w0, w1;
;                 w0.x = cvtpk(o[db][cb][8 * p] * inv, o[db][cb][8 * p + 1] * inv); w0.y = cvtpk(o[db][cb][8 * p + 2] * inv, o[db][cb][8 * p + 3] * inv);
;                 w1.x = cvtpk(o[db][cb][8 * p + 4] * inv, o[db][cb][8 * p + 5] * inv); w1.y = cvtpk(o[db][cb][8 * p + 6] * inv, o[db][cb][8 * p + 7] * inv);
;                 const auto sx = __builtin_amdgcn_permlane32_swap(w0.x, w1.x, false, false), sy = __builtin_amdgcn_permlane32_swap(w0.y, w1.y, false, false);
;                 u32x4 w; w.x = sx[0]; w.y = sy[0]; w.z = sx[1]; w.w = sy[1];
;                 *(u32x4*)(orow + 32 * db + 8 * (2 * p + hh)) = w; }
;     }
	global_store_dwordx4 v[24:25], v[18:21], off
	v_pk_mul_f32 v[26:27], v[80:81], v[0:1] op_sel_hi:[1,0]
	s_and_b64 vcc, exec, s[70:71]
	v_pk_mul_f32 v[18:19], v[74:75], v[0:1] op_sel_hi:[1,0]
	v_pk_mul_f32 v[20:21], v[76:77], v[0:1] op_sel_hi:[1,0]
	v_cvt_pk_bf16_f32 v18, v18, v19
	v_cvt_pk_bf16_f32 v19, v20, v21
	v_pk_mul_f32 v[20:21], v[78:79], v[0:1] op_sel_hi:[1,0]
	v_readlane_b32 s41, v250, 18
	v_cvt_pk_bf16_f32 v20, v20, v21
	v_cvt_pk_bf16_f32 v21, v26, v27
	s_nop 0
	v_permlane32_swap_b32_e32 v18, v20
	v_permlane32_swap_b32_e32 v19, v21
	global_store_dwordx4 v[24:25], v[18:21], off offset:32
	v_pk_mul_f32 v[26:27], v[56:57], v[0:1] op_sel_hi:[1,0]
	s_nop 0
	v_pk_mul_f32 v[18:19], v[50:51], v[0:1] op_sel_hi:[1,0]
	v_pk_mul_f32 v[20:21], v[52:53], v[0:1] op_sel_hi:[1,0]
	v_cvt_pk_bf16_f32 v18, v18, v19
	v_cvt_pk_bf16_f32 v19, v20, v21
	v_pk_mul_f32 v[20:21], v[54:55], v[0:1] op_sel_hi:[1,0]
	s_nop 0
	v_cvt_pk_bf16_f32 v20, v20, v21
	v_cvt_pk_bf16_f32 v21, v26, v27
	s_nop 0
	v_permlane32_swap_b32_e32 v18, v20
	v_permlane32_swap_b32_e32 v19, v21
	global_store_dwordx4 v[24:25], v[18:21], off offset:64
	v_pk_mul_f32 v[26:27], v[64:65], v[0:1] op_sel_hi:[1,0]
	s_nop 0
	v_pk_mul_f32 v[18:19], v[58:59], v[0:1] op_sel_hi:[1,0]
	v_pk_mul_f32 v[20:21], v[60:61], v[0:1] op_sel_hi:[1,0]
	v_cvt_pk_bf16_f32 v18, v18, v19
	v_cvt_pk_bf16_f32 v19, v20, v21
	v_pk_mul_f32 v[20:21], v[62:63], v[0:1] op_sel_hi:[1,0]
	ds_bpermute_b32 v0, v190, v182
	v_cvt_pk_bf16_f32 v20, v20, v21
	v_cvt_pk_bf16_f32 v21, v26, v27
	s_nop 0
	v_permlane32_swap_b32_e32 v18, v20
	s_waitcnt lgkmcnt(0)
	v_add_f32_e32 v0, v182, v0
	v_add_f32_e32 v0, v28, v0
	v_permlane32_swap_b32_e32 v19, v21
	v_rcp_f32_e32 v0, v0
	global_store_dwordx4 v[24:25], v[18:21], off offset:96
	v_pk_mul_f32 v[2:3], v[2:3], v[0:1] op_sel_hi:[1,0]
	s_nop 0
	v_or_b32_e32 v18, 32, v22
	v_ashrrev_i32_e32 v19, 31, v18
	v_lshlrev_b64 v[18:19], 11, v[18:19]
	v_lshl_add_u64 v[22:23], s[80:81], 0, v[18:19]
	v_pk_mul_f32 v[18:19], v[34:35], v[0:1] op_sel_hi:[1,0]
	v_pk_mul_f32 v[20:21], v[36:37], v[0:1] op_sel_hi:[1,0]
	v_pk_mul_f32 v[4:5], v[4:5], v[0:1] op_sel_hi:[1,0]
	v_cvt_pk_bf16_f32 v18, v18, v19
	v_cvt_pk_bf16_f32 v19, v20, v21
	v_pk_mul_f32 v[20:21], v[38:39], v[0:1] op_sel_hi:[1,0]
	v_pk_mul_f32 v[24:25], v[40:41], v[0:1] op_sel_hi:[1,0]
	v_cvt_pk_bf16_f32 v2, v2, v3
	v_cvt_pk_bf16_f32 v3, v4, v5
	v_pk_mul_f32 v[4:5], v[6:7], v[0:1] op_sel_hi:[1,0]
	v_pk_mul_f32 v[6:7], v[8:9], v[0:1] op_sel_hi:[1,0]
	v_cvt_pk_bf16_f32 v20, v20, v21
	v_cvt_pk_bf16_f32 v21, v24, v25
	v_cvt_pk_bf16_f32 v4, v4, v5
	v_cvt_pk_bf16_f32 v5, v6, v7
	v_permlane32_swap_b32_e32 v18, v20
	v_permlane32_swap_b32_e32 v19, v21
	v_lshl_add_u64 v[22:23], v[22:23], 0, v[176:177]
	v_permlane32_swap_b32_e32 v2, v4
	v_permlane32_swap_b32_e32 v3, v5
	global_store_dwordx4 v[22:23], v[18:21], off
	global_store_dwordx4 v[22:23], v[2:5], off offset:64
	v_pk_mul_f32 v[24:25], v[48:49], v[0:1] op_sel_hi:[1,0]
	v_pk_mul_f32 v[18:19], v[42:43], v[0:1] op_sel_hi:[1,0]
	v_pk_mul_f32 v[20:21], v[44:45], v[0:1] op_sel_hi:[1,0]
	v_pk_mul_f32 v[2:3], v[10:11], v[0:1] op_sel_hi:[1,0]
	v_pk_mul_f32 v[4:5], v[12:13], v[0:1] op_sel_hi:[1,0]
	v_cvt_pk_bf16_f32 v18, v18, v19
	v_cvt_pk_bf16_f32 v19, v20, v21
	v_pk_mul_f32 v[20:21], v[46:47], v[0:1] op_sel_hi:[1,0]
	v_cvt_pk_bf16_f32 v2, v2, v3
	v_cvt_pk_bf16_f32 v3, v4, v5
	v_pk_mul_f32 v[4:5], v[14:15], v[0:1] op_sel_hi:[1,0]
	v_pk_mul_f32 v[6:7], v[16:17], v[0:1] op_sel_hi:[1,0]
	v_cvt_pk_bf16_f32 v20, v20, v21
	v_cvt_pk_bf16_f32 v21, v24, v25
	v_cvt_pk_bf16_f32 v4, v4, v5
	v_cvt_pk_bf16_f32 v5, v6, v7
	v_permlane32_swap_b32_e32 v18, v20
	v_permlane32_swap_b32_e32 v19, v21
	v_permlane32_swap_b32_e32 v2, v4
	v_permlane32_swap_b32_e32 v3, v5
	global_store_dwordx4 v[22:23], v[18:21], off offset:32
	global_store_dwordx4 v[22:23], v[2:5], off offset:96
	s_cbranch_vccz .LBB9_308
